# SwiGLU epilogue: per-row rstd cached in AGPRs across units that keep the row tile; x->XB prologue loop hand-pipelined
# speedup vs baseline: 1.0279x; 1.0139x over previous
; #define INP(i) ((const float*)karg(8 * (i)))
; #define WSP() ((unsigned char*)karg(168))
; DI void prologue(const Args& A, unsigned char* lds, int wave, int lane) {
;     ...
;     const float* x = INP(0); bf16* XB = (bf16*)(WSP() + WS_XB); float* ssq = (float*)(WSP() + WS_SSQ);
;     for (int m = gw; m < M; m += NGW) {
;         const f32x4* xr = (const f32x4*)(x + (size_t)m * DM) + lane; f32x4 v[4]; float s = 0.f;
; #pragma unroll
;         for (int j = 0; j < 4; ++j) { v[j] = xr[64 * j]; s += (v[j][0] * v[j][0] + v[j][1] * v[j][1]) + (v[j][2] * v[j][2] + v[j][3] * v[j][3]); }
;         s = wave_sum(s);
;         u32x2* o = (u32x2*)(XB + (size_t)m * DM) + lane;
.LBB0_80:
	s_mov_b32 s9, 0
	s_movk_i32 s4, 0xa8
	s_movk_i32 s5, 0xa8
	s_cmpk_gt_i32 s8, 0x7fff
	v_mbcnt_lo_u32_b32 v8, -1, 0
	s_cbranch_scc1 .LBB0_85
	v_mbcnt_hi_u32_b32 v2, -1, v8
	v_and_b32_e32 v3, 64, v2
	v_add_u32_e32 v3, 64, v3
	v_xor_b32_e32 v4, 1, v2
	v_cmp_lt_i32_e32 vcc, v4, v3
	s_ashr_i32 s11, s9, 31
	s_add_u32 s10, s0, s9
	v_cndmask_b32_e32 v4, v2, v4, vcc
	v_lshlrev_b32_e32 v9, 2, v4
	v_xor_b32_e32 v4, 2, v2
	v_cmp_lt_i32_e32 vcc, v4, v3
	s_addc_u32 s11, s1, s11
	s_ashr_i32 s9, s5, 31
	v_cndmask_b32_e32 v4, v2, v4, vcc
	v_lshlrev_b32_e32 v10, 2, v4
	v_xor_b32_e32 v4, 4, v2
	v_cmp_lt_i32_e32 vcc, v4, v3
	s_add_u32 s12, s0, s5
	s_addc_u32 s13, s1, s9
	v_cndmask_b32_e32 v4, v2, v4, vcc
	s_ashr_i32 s5, s4, 31
	v_lshlrev_b32_e32 v11, 2, v4
	v_xor_b32_e32 v4, 8, v2
	s_add_u32 s4, s0, s4
	v_cmp_lt_i32_e32 vcc, v4, v3
	s_addc_u32 s5, s1, s5
	s_load_dwordx2 s[14:15], s[10:11], 0x0
	s_load_dwordx2 s[16:17], s[12:13], 0x0
	s_load_dwordx2 s[18:19], s[4:5], 0x0
	v_cndmask_b32_e32 v4, v2, v4, vcc
	v_lshlrev_b32_e32 v12, 2, v4
	v_xor_b32_e32 v4, 16, v2
	v_cmp_lt_i32_e32 vcc, v4, v3
	s_ashr_i32 s9, s8, 31
	s_lshl_b64 s[10:11], s[8:9], 6
	v_cndmask_b32_e32 v4, v2, v4, vcc
	v_lshlrev_b32_e32 v13, 2, v4
	v_xor_b32_e32 v4, 32, v2
	v_cmp_lt_i32_e32 vcc, v4, v3
	s_waitcnt lgkmcnt(0)
	s_add_u32 s10, s18, s10
	v_mov_b32_e32 v15, 0
	v_cndmask_b32_e32 v2, v2, v4, vcc
	s_addc_u32 s11, s19, s11
	v_lshlrev_b32_e32 v18, 2, v2
	v_lshl_add_u64 v[2:3], s[10:11], 0, v[14:15]
	s_mov_b64 s[10:11], 0x9400000
	s_ashr_i32 s43, s42, 31
	v_lshl_add_u64 v[2:3], v[2:3], 0, s[10:11]
	s_lshl_b64 s[10:11], s[42:43], 6
	s_lshl_b64 s[12:13], s[8:9], 11
	s_add_u32 s12, s16, s12
	v_mov_b32_e32 v17, v15
	s_addc_u32 s13, s17, s13
	v_lshl_add_u64 v[4:5], s[12:13], 0, v[16:17]
	s_mov_b64 s[12:13], 0x5400600
	v_lshl_add_u64 v[4:5], v[4:5], 0, s[12:13]
	s_lshl_b64 s[12:13], s[42:43], 11
	s_lshl_b64 s[16:17], s[8:9], 12
	s_add_u32 s14, s14, s16
	v_lshlrev_b32_e32 v14, 4, v1
	s_addc_u32 s15, s15, s17
	v_lshl_add_u64 v[6:7], s[14:15], 0, v[14:15]
	s_mov_b64 s[14:15], 0x800
	v_cmp_gt_u32_e32 vcc, 16, v1
	v_cmp_eq_u32_e64 s[4:5], 0, v1
	v_lshl_add_u64 v[6:7], v[6:7], 0, s[14:15]
	s_lshl_b64 s[14:15], s[42:43], 12
	s_waitcnt lgkmcnt(0)
	global_load_dwordx4 v[14:17], v[6:7], off offset:-2048
	global_load_dwordx4 v[18:21], v[6:7], off offset:-1024
	global_load_dwordx4 v[22:25], v[6:7], off
	global_load_dwordx4 v[26:29], v[6:7], off offset:1024
; DI unsigned pk2(float lo, float hi) { return pg8::cvt_pk_bf16(lo, hi); }
; #define INP(i) ((const float*)karg(8 * (i)))
; #define WSP() ((unsigned char*)karg(168))
; DI void prologue(const Args& A, unsigned char* lds, int wave, int lane) {
;     ...
;     const float* x = INP(0); bf16* XB = (bf16*)(WSP() + WS_XB); float* ssq = (float*)(WSP() + WS_SSQ);
;     for (int m = gw; m < M; m += NGW) {
;         const f32x4* xr = (const f32x4*)(x + (size_t)m * DM) + lane; f32x4 v[4]; float s = 0.f;
; #pragma unroll
;         for (int j = 0; j < 4; ++j) { v[j] = xr[64 * j]; s += (v[j][0] * v[j][0] + v[j][1] * v[j][1]) + (v[j][2] * v[j][2] + v[j][3] * v[j][3]); }
;         s = wave_sum(s);
;         u32x2* o = (u32x2*)(XB + (size_t)m * DM) + lane;
; #pragma unroll
;         for (int j = 0; j < 4; ++j) { u32x2 w; w.x = pk2(v[j][0], v[j][1]); w.y = pk2(v[j][2], v[j][3]); o[64 * j] = w; }
;         if (lane < 16) ssq[(size_t)m * 16 + lane] = lane == 0 ? s : 0.f;
;     }
.Lx_A:
	s_add_i32 s8, s8, s42
	s_cmp_lt_i32 s8, 0x8000
	s_cselect_b32 s20, s14, 0
	s_cselect_b32 s21, s15, 0
	s_cselect_b64 s[22:23], -1, 0
	v_lshl_add_u64 v[6:7], v[6:7], 0, s[20:21]
	global_load_dwordx4 v[40:43], v[6:7], off offset:-2048
	global_load_dwordx4 v[44:47], v[6:7], off offset:-1024
	global_load_dwordx4 v[48:51], v[6:7], off
	global_load_dwordx4 v[52:55], v[6:7], off offset:1024
	s_waitcnt vmcnt(4)
	v_mul_f32_e32 v1, v15, v15
	v_mul_f32_e32 v59, v17, v17
	v_mul_f32_e32 v56, v19, v19
	v_mul_f32_e32 v60, v21, v21
	v_mul_f32_e32 v57, v23, v23
	v_mul_f32_e32 v61, v25, v25
	v_mul_f32_e32 v58, v27, v27
	v_mul_f32_e32 v62, v29, v29
	v_fmac_f32_e32 v1, v14, v14
	v_fmac_f32_e32 v59, v16, v16
	v_fmac_f32_e32 v56, v18, v18
	v_fmac_f32_e32 v60, v20, v20
	v_fmac_f32_e32 v57, v22, v22
	v_fmac_f32_e32 v61, v24, v24
	v_fmac_f32_e32 v58, v26, v26
	v_fmac_f32_e32 v62, v28, v28
	v_add_f32_e32 v1, v1, v59
	v_add_f32_e32 v56, v56, v60
	v_add_f32_e32 v57, v57, v61
	v_add_f32_e32 v58, v58, v62
	v_add_f32_e32 v1, v1, v56
	v_add_f32_e32 v1, v1, v57
	v_add_f32_e32 v1, v1, v58
	v_cvt_pk_bf16_f32 v30, v14, v15
	v_cvt_pk_bf16_f32 v31, v16, v17
	v_cvt_pk_bf16_f32 v32, v18, v19
	v_cvt_pk_bf16_f32 v33, v20, v21
	v_cvt_pk_bf16_f32 v34, v22, v23
	v_cvt_pk_bf16_f32 v35, v24, v25
	v_cvt_pk_bf16_f32 v36, v26, v27
	v_cvt_pk_bf16_f32 v37, v28, v29
	s_nop 1
	v_add_f32_dpp v1, v1, v1 quad_perm:[1,0,3,2] row_mask:0xf bank_mask:0xf
	s_nop 1
	v_add_f32_dpp v1, v1, v1 quad_perm:[2,3,0,1] row_mask:0xf bank_mask:0xf
	s_nop 1
	v_add_f32_dpp v1, v1, v1 row_half_mirror row_mask:0xf bank_mask:0xf
	s_nop 1
	v_add_f32_dpp v1, v1, v1 row_mirror row_mask:0xf bank_mask:0xf
	v_mov_b32_e32 v38, v1
	v_mov_b32_e32 v39, v1
	s_nop 1
	v_permlane16_swap_b32 v38, v39
	v_add_f32_e32 v1, v38, v39
	v_mov_b32_e32 v38, v1
	v_mov_b32_e32 v39, v1
	s_nop 1
	v_permlane32_swap_b32 v38, v39
	v_add_f32_e32 v1, v38, v39
	global_store_dwordx2 v[4:5], v[30:31], off offset:-1536
	global_store_dwordx2 v[4:5], v[32:33], off offset:-1024
	global_store_dwordx2 v[4:5], v[34:35], off offset:-512
	global_store_dwordx2 v[4:5], v[36:37], off
	v_cndmask_b32_e64 v1, 0, v1, s[4:5]
	s_and_saveexec_b64 s[16:17], vcc
	global_store_dword v[2:3], v1, off
	s_or_b64 exec, exec, s[16:17]
	v_lshl_add_u64 v[2:3], v[2:3], 0, s[10:11]
	v_lshl_add_u64 v[4:5], v[4:5], 0, s[12:13]
	s_and_b64 s[20:21], s[22:23], exec
	s_cbranch_scc0 .Lx_done
	s_add_i32 s8, s8, s42
	s_cmp_lt_i32 s8, 0x8000
	s_cselect_b32 s20, s14, 0
	s_cselect_b32 s21, s15, 0
	s_cselect_b64 s[22:23], -1, 0
	v_lshl_add_u64 v[6:7], v[6:7], 0, s[20:21]
	global_load_dwordx4 v[14:17], v[6:7], off offset:-2048
	global_load_dwordx4 v[18:21], v[6:7], off offset:-1024
	global_load_dwordx4 v[22:25], v[6:7], off
	global_load_dwordx4 v[26:29], v[6:7], off offset:1024
	s_waitcnt vmcnt(4)
	v_mul_f32_e32 v1, v41, v41
	v_mul_f32_e32 v59, v43, v43
	v_mul_f32_e32 v56, v45, v45
	v_mul_f32_e32 v60, v47, v47
	v_mul_f32_e32 v57, v49, v49
	v_mul_f32_e32 v61, v51, v51
	v_mul_f32_e32 v58, v53, v53
	v_mul_f32_e32 v62, v55, v55
	v_fmac_f32_e32 v1, v40, v40
	v_fmac_f32_e32 v59, v42, v42
	v_fmac_f32_e32 v56, v44, v44
	v_fmac_f32_e32 v60, v46, v46
	v_fmac_f32_e32 v57, v48, v48
	v_fmac_f32_e32 v61, v50, v50
	v_fmac_f32_e32 v58, v52, v52
	v_fmac_f32_e32 v62, v54, v54
	v_add_f32_e32 v1, v1, v59
	v_add_f32_e32 v56, v56, v60
	v_add_f32_e32 v57, v57, v61
	v_add_f32_e32 v58, v58, v62
	v_add_f32_e32 v1, v1, v56
	v_add_f32_e32 v1, v1, v57
	v_add_f32_e32 v1, v1, v58
	v_cvt_pk_bf16_f32 v30, v40, v41
	v_cvt_pk_bf16_f32 v31, v42, v43
	v_cvt_pk_bf16_f32 v32, v44, v45
	v_cvt_pk_bf16_f32 v33, v46, v47
	v_cvt_pk_bf16_f32 v34, v48, v49
	v_cvt_pk_bf16_f32 v35, v50, v51
	v_cvt_pk_bf16_f32 v36, v52, v53
	v_cvt_pk_bf16_f32 v37, v54, v55
	s_nop 1
	v_add_f32_dpp v1, v1, v1 quad_perm:[1,0,3,2] row_mask:0xf bank_mask:0xf
	s_nop 1
	v_add_f32_dpp v1, v1, v1 quad_perm:[2,3,0,1] row_mask:0xf bank_mask:0xf
	s_nop 1
	v_add_f32_dpp v1, v1, v1 row_half_mirror row_mask:0xf bank_mask:0xf
	s_nop 1
	v_add_f32_dpp v1, v1, v1 row_mirror row_mask:0xf bank_mask:0xf
	v_mov_b32_e32 v38, v1
	v_mov_b32_e32 v39, v1
	s_nop 1
	v_permlane16_swap_b32 v38, v39
	v_add_f32_e32 v1, v38, v39
	v_mov_b32_e32 v38, v1
	v_mov_b32_e32 v39, v1
	s_nop 1
	v_permlane32_swap_b32 v38, v39
	v_add_f32_e32 v1, v38, v39
	global_store_dwordx2 v[4:5], v[30:31], off offset:-1536
	global_store_dwordx2 v[4:5], v[32:33], off offset:-1024
	global_store_dwordx2 v[4:5], v[34:35], off offset:-512
	global_store_dwordx2 v[4:5], v[36:37], off
	v_cndmask_b32_e64 v1, 0, v1, s[4:5]
	s_and_saveexec_b64 s[16:17], vcc
	global_store_dword v[2:3], v1, off
	s_or_b64 exec, exec, s[16:17]
	v_lshl_add_u64 v[2:3], v[2:3], 0, s[10:11]
	v_lshl_add_u64 v[4:5], v[4:5], 0, s[12:13]
	s_and_b64 s[20:21], s[22:23], exec
	s_cbranch_scc1 .Lx_A
.Lx_done:
	s_waitcnt vmcnt(0)
.LBB0_85:
	s_cmp_lt_i32 s80, 0x100001
	s_cbranch_scc1 .LBB0_97
	v_lshrrev_b32_e32 v1, 20, v0
	v_lshrrev_b32_e32 v0, 10, v0
	v_or_b32_e32 v0, v0, v1
	s_movk_i32 s4, 0x3ff
	v_and_or_b32 v0, v0, s4, v165
	v_cmp_eq_u32_e32 vcc, 0, v0
	s_waitcnt lgkmcnt(0)
	s_barrier
	s_and_saveexec_b64 s[4:5], vcc
	s_cbranch_execz .LBB0_96
	buffer_wbl2 sc1
	s_waitcnt vmcnt(0)
	s_load_dwordx2 s[6:7], s[6:7], 0x58
	v_mov_b32_e32 v2, 0
	s_mov_b64 s[8:9], exec
	v_mbcnt_lo_u32_b32 v1, s8, 0
	v_mbcnt_hi_u32_b32 v1, s9, v1
	s_waitcnt lgkmcnt(0)
	global_load_dword v0, v2, s[6:7] offset:40
	v_cmp_eq_u32_e32 vcc, 0, v1
	s_and_saveexec_b64 s[10:11], vcc
	s_cbranch_execz .LBB0_89
	s_bcnt1_i32_b64 s8, s[8:9]
	v_mov_b32_e32 v3, s8
	global_atomic_add v3, v2, v3, s[6:7] offset:32 sc0

; #define PG8_STAGE(bufoff, gbase, voff) do { _Pragma("unroll") for (int _i = 0; _i < 2; ++_i) \
;         __builtin_amdgcn_global_load_lds((const unsigned*)((const char*)(gbase) + (voff)[_i]), (PG8_LAS unsigned*)(lds + (bufoff) + ldsw + _i * 8192), 16, 0, 0); } while (0)
; #define PG8_WAIT_V(n) asm volatile("s_waitcnt vmcnt(" #n ")" ::: "memory")
; #define PG8_BAR __builtin_amdgcn_s_barrier()
; template <class Epi, class Sched, bool ALIGN_EPI = false, bool SP2 = false>
; __device__ __forceinline__ void gemm_phase(PG8_LAS unsigned char* lds, const Gemm g, const Sched& S, const Epi& E) {
;     ...
;     for (int i = 0; i < 2; ++i) { int R, C; stage_rc(tid * 16 + i * 8192, R, C); const int Rb = Epi::PERM ? ((R & ~31) + perm32(R & 31)) : R;
;         voffA[i] = (unsigned)(R * K + C) * 2u; voffB[i] = (unsigned)(Rb * K + C) * 2u; }
;     const size_t kstep = (size_t)(BK * 2);
;     const size_t hstep = (size_t)HALF * K * 2;
;     const size_t tstep = 2 * hstep;
;     const unsigned ldsw = (unsigned)wid * 1024u;
;     const int aoff = lds_byte(wr * 64 + fr, fq * 8), boff = lds_byte(wc * 32 + fr, fq * 8);
;     ...
;     Unit cur, nxt; int ui = 0;
;     if (!S.next(0, cur)) return;
;     f32x4 acc[2][2][4][2];
; #pragma unroll
;     for (int a = 0; a < 2; ++a)
; #pragma unroll
;         for (int b = 0; b < 2; ++b)
; #pragma unroll
;             for (int m = 0; m < 4; ++m)
; #pragma unroll
;                 for (int n = 0; n < 2; ++n) acc[a][b][m][n] = (f32x4){0.f, 0.f, 0.f, 0.f};
;     bf16x8 At[4][2], B0[2][2], B1[2][2];
;     const char* cA = (const char*)g.A + (size_t)cur.pm * tstep; const char* cB = (const char*)g.Bt + (size_t)cur.pn * tstep;
;     S.a_ready(cur);
;     if constexpr (SP2) {
;         PG8_STAGE(PG8_SB(0, 0), cB, voffB); PG8_STAGE(PG8_SB(0, 1), cB + hstep, voffB); PG8_STAGE(PG8_SA(0, 0), cA, voffA); PG8_STAGE(PG8_SA(0, 1), cA + hstep, voffA);
;         if (wr == 1) PG8_BAR;
;         PG8_WAIT_V(2); PG8_BAR;
;         PG8_STAGE(PG8_SB(1, 0), cB + kstep, voffB); PG8_STAGE(PG8_SA(1, 0), cA + kstep, voffA); PG8_STAGE(PG8_SB(1, 1), cB + hstep + kstep, voffB);
;         PG8_WAIT_V(6); PG8_BAR;
.LBB0_160:
	v_readlane_b32 s50, v245, 24
	s_lshl_b32 s14, s14, 5
	v_mov_b32_e32 v139, v1
	v_readlane_b32 s51, v245, 25
	s_and_b32 s23, s14, 0x60
	s_add_i32 m0, s10, 0x18000
	v_lshl_add_u64 v[2:3], v[2:3], 0, s[20:21]
	v_lshl_add_u64 v[14:15], s[50:51], 0, v[138:139]
	v_mov_b32_e32 v137, v1
	s_lshl_b32 s22, s3, 13
	s_lshl_b32 s40, s23, 7
	s_waitcnt vmcnt(2)
	s_barrier
	global_load_lds_dwordx4 v[2:3], off
	v_lshl_add_u64 v[2:3], v[4:5], 0, s[20:21]
	s_add_i32 m0, s10, 0x1a000
	s_add_i32 s54, s10, 0x8000
	s_add_i32 s55, s10, 0xa000
	v_lshl_add_u64 v[16:17], s[50:51], 0, v[136:137]
	global_load_lds_dwordx4 v[2:3], off
	v_lshl_add_u64 v[2:3], v[14:15], 0, s[20:21]
	s_mov_b32 m0, s54
	s_add_u32 s14, s12, 0x40080
	global_load_lds_dwordx4 v[2:3], off
	v_lshl_add_u64 v[2:3], v[16:17], 0, s[20:21]
	s_mov_b32 m0, s55
	s_addc_u32 s15, s13, 0
	global_load_lds_dwordx4 v[2:3], off
	s_add_i32 m0, s10, 0x1c000
	v_lshl_add_u64 v[2:3], s[14:15], 0, v[0:1]
	global_load_lds_dwordx4 v[2:3], off
	v_lshl_add_u64 v[2:3], s[14:15], 0, v[134:135]
	s_add_i32 m0, s10, 0x1e000
	v_bfe_u32 v4, v7, 4, 2
	global_load_lds_dwordx4 v[2:3], off
	v_and_b32_e32 v3, 15, v7
	v_lshlrev_b32_e32 v2, 4, v4
	v_lshlrev_b32_e32 v5, 2, v7
	v_lshl_or_b32 v182, s3, 6, v3
	v_lshl_or_b32 v3, v3, 6, v2
	v_and_b32_e32 v5, 32, v5
	v_bitop3_b32 v7, v3, s22, v5 bitop3:0xde
	v_bitop3_b32 v183, v3, s40, v5 bitop3:0xde
	v_mov_b32_e32 v3, v1
	v_lshl_add_u64 v[140:141], s[88:89], 0, v[2:3]
	v_lshlrev_b32_e32 v2, 14, v11
	v_and_b32_e32 v2, 0xffff8000, v2
	v_lshl_add_u32 v2, v10, 11, v2
	v_and_b32_e32 v3, 1, v11
	v_lshl_or_b32 v2, v3, 6, v2
	v_lshl_add_u32 v142, v12, 1, v2
	v_lshlrev_b32_e32 v2, 14, v6
	v_and_b32_e32 v2, 0xffff8000, v2
	s_waitcnt vmcnt(6)
	s_cmpk_lt_u32 s2, 0x100
	v_lshl_add_u32 v2, v8, 11, v2
	v_and_b32_e32 v3, 1, v6
	v_readlane_b32 s2, v245, 22
	v_lshl_or_b32 v2, v3, 6, v2
	v_readlane_b32 s3, v245, 23
	s_cselect_b64 s[42:43], -1, 0
	v_lshl_or_b32 v184, v4, 3, s23
	v_mov_b32_e32 v143, v1
	v_lshl_add_u32 v144, v9, 1, v2
	v_mov_b32_e32 v145, v1
	s_mov_b32 s56, 0
	v_add_u32_e32 v185, 0, v7
	v_readlane_b32 s57, v245, 19
	s_mov_b32 s58, s2
	s_mov_b64 s[2:3], s[50:51]
	s_barrier
	s_mov_b32 s98, -1
	s_branch .LBB0_163

; DI void row_rstd(const float* ssq, int row0, int fq, float (&rs)[2][4]) {
; #pragma unroll
;     for (int ai = 0; ai < 2; ++ai)
; #pragma unroll
;         for (int m = 0; m < 4; ++m) {
;             const f32x4 v = *(const f32x4*)(ssq + (size_t)(row0 + ai * 128 + m * 16) * 16 + 4 * fq);
;             float s = (v[0] + v[1]) + (v[2] + v[3]);
;             s += __shfl_xor(s, 16); s += __shfl_xor(s, 32);
;             rs[ai][m] = rsqrtf(s * (1.0f / DM) + EPS);
;         }
; }
;     DI void operator()(const f32x4 (&acc)[2][2][4][2], const pg8::Unit& u, int wr, int wc, int fr, int fq) const {
;         const int row0 = u.pm * 256 + wr * 64 + fr, col0 = u.pn * 128 + wc * 32 + 8 * fq;
;         float rs[2][4]; row_rstd(ssq, row0, fq, rs);
; #pragma unroll
;         for (int ai = 0; ai < 2; ++ai)
; #pragma unroll
;             for (int m = 0; m < 4; ++m) {
;                 typedef float f32x2 __attribute__((ext_vector_type(2)));
;                 const float r = rs[ai][m]; const float r2s = r * r, rls = r * -1.44269504f; const f32x2 r2 = {r2s, r2s}, rl = {rls, rls};
.LBB0_169:
	v_and_b32_e32 v131, 64, v194
	v_xor_b32_e32 v130, 16, v194
	v_add_u32_e32 v131, 64, v131
	v_cmp_lt_i32_e32 vcc, v130, v131
	v_lshl_add_u32 v160, s58, 8, v182
	v_ashrrev_i32_e32 v161, 31, v160
	v_cndmask_b32_e32 v130, v194, v130, vcc
	v_lshlrev_b32_e32 v186, 2, v130
	v_xor_b32_e32 v130, 32, v194
	v_cmp_lt_i32_e32 vcc, v130, v131
	v_or_b32_e32 v158, 16, v160
	v_ashrrev_i32_e32 v159, 31, v158
	v_cndmask_b32_e32 v130, v194, v130, vcc
	v_lshlrev_b32_e32 v163, 2, v130
	v_lshlrev_b64 v[130:131], 6, v[160:161]
	v_lshl_add_u64 v[130:131], v[140:141], 0, v[130:131]
	v_mov_b64_e32 v[178:179], s[16:17]
	v_or_b32_e32 v156, 32, v160
	v_ashrrev_i32_e32 v157, 31, v156
	v_or_b32_e32 v154, 48, v160
	v_ashrrev_i32_e32 v155, 31, v154
	v_add_u32_e32 v152, 0x80, v160
	v_ashrrev_i32_e32 v153, 31, v152
	v_add_u32_e32 v150, 0x90, v160
	v_ashrrev_i32_e32 v151, 31, v150
	v_pk_mul_f32 v[122:123], v[126:127], v[122:123]
	v_pk_mul_f32 v[124:125], v[128:129], v[124:125]
	v_pk_mul_f32 v[114:115], v[118:119], v[114:115]
	v_pk_mul_f32 v[116:117], v[120:121], v[116:117]
	v_lshl_or_b32 v162, s57, 7, v184
	v_pk_mul_f32 v[106:107], v[110:111], v[106:107]
	v_pk_mul_f32 v[108:109], v[112:113], v[108:109]
	v_pk_mul_f32 v[98:99], v[102:103], v[98:99]
	v_pk_mul_f32 v[100:101], v[104:105], v[100:101]
	v_pk_mul_f32 v[90:91], v[94:95], v[90:91]
	v_pk_mul_f32 v[92:93], v[96:97], v[92:93]
	v_pk_mul_f32 v[82:83], v[86:87], v[82:83]
	v_pk_mul_f32 v[84:85], v[88:89], v[84:85]
	v_pk_mul_f32 v[74:75], v[78:79], v[74:75]
	v_pk_mul_f32 v[76:77], v[80:81], v[76:77]
	v_pk_mul_f32 v[66:67], v[70:71], v[66:67]
	v_pk_mul_f32 v[68:69], v[72:73], v[68:69]
	v_pk_mul_f32 v[58:59], v[62:63], v[58:59]
	v_pk_mul_f32 v[60:61], v[64:65], v[60:61]
	v_pk_mul_f32 v[50:51], v[54:55], v[50:51]
	v_pk_mul_f32 v[52:53], v[56:57], v[52:53]
	v_pk_mul_f32 v[42:43], v[46:47], v[42:43]
	v_pk_mul_f32 v[44:45], v[48:49], v[44:45]
	v_pk_mul_f32 v[34:35], v[38:39], v[34:35]
	v_pk_mul_f32 v[36:37], v[40:41], v[36:37]
	v_pk_mul_f32 v[26:27], v[30:31], v[26:27]
	v_pk_mul_f32 v[28:29], v[32:33], v[28:29]
	v_pk_mul_f32 v[18:19], v[22:23], v[18:19]
	v_pk_mul_f32 v[20:21], v[24:25], v[20:21]
	v_pk_mul_f32 v[10:11], v[14:15], v[10:11]
	v_pk_mul_f32 v[12:13], v[16:17], v[12:13]
	v_pk_mul_f32 v[2:3], v[6:7], v[2:3]
	v_pk_mul_f32 v[4:5], v[8:9], v[4:5]
	s_cmp_eq_u32 s58, s98
	s_cbranch_scc1 .Lrc_hit_0
	s_waitcnt vmcnt(7)
	v_mov_b32_e32 v130, v202
	v_mov_b32_e32 v131, v203
	v_mov_b32_e32 v132, v204
	v_mov_b32_e32 v133, v205
	v_mov_b32_e32 v146, v131
	v_mov_b32_e32 v147, v132
	v_mov_b32_e32 v131, v133
	v_pk_add_f32 v[146:147], v[146:147], v[130:131]
	v_lshlrev_b64 v[130:131], 6, v[158:159]
	v_lshl_add_u64 v[130:131], v[140:141], 0, v[130:131]
	s_waitcnt vmcnt(6)
	v_mov_b32_e32 v130, v206
	v_mov_b32_e32 v131, v207
	v_mov_b32_e32 v132, v208
	v_mov_b32_e32 v133, v209
	v_mov_b32_e32 v148, v131
	v_mov_b32_e32 v149, v132
	v_mov_b32_e32 v131, v133
	v_pk_add_f32 v[130:131], v[148:149], v[130:131]
	v_mov_b32_e32 v133, v146
	v_mov_b32_e32 v132, v130
	v_mov_b32_e32 v146, v131
	v_pk_add_f32 v[130:131], v[132:133], v[146:147]
	ds_bpermute_b32 v133, v186, v131
	ds_bpermute_b32 v132, v186, v130
	s_waitcnt lgkmcnt(0)
	v_pk_add_f32 v[130:131], v[130:131], v[132:133]
	ds_bpermute_b32 v133, v163, v131
	ds_bpermute_b32 v132, v163, v130
	s_waitcnt lgkmcnt(0)
	v_pk_add_f32 v[130:131], v[130:131], v[132:133]
	s_nop 0
	v_pk_fma_f32 v[130:131], v[130:131], s[34:35], v[178:179] op_sel_hi:[1,0,0]
	s_nop 0
	v_mul_f32_e32 v132, 0x4b800000, v131
	v_cmp_gt_f32_e64 s[2:3], s25, v131
	v_cmp_gt_f32_e32 vcc, s25, v130
	s_nop 0
	v_cndmask_b32_e64 v131, v131, v132, s[2:3]
	v_rsq_f32_e32 v131, v131
	s_nop 0
	v_mul_f32_e32 v132, 0x45800000, v131
	v_cndmask_b32_e64 v161, v131, v132, s[2:3]
	v_mul_f32_e32 v131, 0x4b800000, v130
	v_cndmask_b32_e32 v130, v130, v131, vcc
	v_rsq_f32_e32 v130, v130
	s_nop 0
	v_mul_f32_e32 v131, 0x45800000, v130
	v_cndmask_b32_e32 v159, v130, v131, vcc
	v_lshlrev_b64 v[130:131], 6, v[156:157]
	v_lshl_add_u64 v[130:131], v[140:141], 0, v[130:131]
	s_waitcnt vmcnt(5)
	v_mov_b32_e32 v130, v210
	v_mov_b32_e32 v131, v211
	v_mov_b32_e32 v132, v212
	v_mov_b32_e32 v133, v213
	v_mov_b32_e32 v146, v131
	v_mov_b32_e32 v147, v132
	v_mov_b32_e32 v131, v133
	v_pk_add_f32 v[146:147], v[146:147], v[130:131]
	v_lshlrev_b64 v[130:131], 6, v[154:155]
	v_lshl_add_u64 v[130:131], v[140:141], 0, v[130:131]
	s_waitcnt vmcnt(4)
	v_mov_b32_e32 v130, v214
	v_mov_b32_e32 v131, v215
	v_mov_b32_e32 v132, v216
	v_mov_b32_e32 v133, v217
	v_mov_b32_e32 v148, v131
	v_mov_b32_e32 v149, v132
	v_mov_b32_e32 v131, v133
	v_pk_add_f32 v[130:131], v[148:149], v[130:131]
	v_mov_b32_e32 v133, v146
	v_mov_b32_e32 v132, v130
	v_mov_b32_e32 v146, v131
	v_pk_add_f32 v[130:131], v[132:133], v[146:147]
	ds_bpermute_b32 v133, v186, v131
	ds_bpermute_b32 v132, v186, v130
	s_waitcnt lgkmcnt(0)
	v_pk_add_f32 v[130:131], v[130:131], v[132:133]
	ds_bpermute_b32 v133, v163, v131
	ds_bpermute_b32 v132, v163, v130
	s_waitcnt lgkmcnt(0)
	v_pk_add_f32 v[130:131], v[130:131], v[132:133]
	s_nop 0
	v_pk_fma_f32 v[130:131], v[130:131], s[34:35], v[178:179] op_sel_hi:[1,0,0]
	s_nop 0
	v_mul_f32_e32 v132, 0x4b800000, v131
	v_cmp_gt_f32_e64 s[2:3], s25, v131
	v_cmp_gt_f32_e32 vcc, s25, v130
	s_nop 0
	v_cndmask_b32_e64 v131, v131, v132, s[2:3]
	v_rsq_f32_e32 v131, v131
	s_nop 0
	v_mul_f32_e32 v132, 0x45800000, v131
	v_cndmask_b32_e64 v157, v131, v132, s[2:3]
	v_mul_f32_e32 v131, 0x4b800000, v130
	v_cndmask_b32_e32 v130, v130, v131, vcc
	v_rsq_f32_e32 v130, v130
	s_nop 0
	v_mul_f32_e32 v131, 0x45800000, v130
	v_cndmask_b32_e32 v155, v130, v131, vcc
	v_lshlrev_b64 v[130:131], 6, v[152:153]
	v_lshl_add_u64 v[130:131], v[140:141], 0, v[130:131]
	s_waitcnt vmcnt(3)
; DI unsigned pk2(float lo, float hi) { return pg8::cvt_pk_bf16(lo, hi); }
; DI void row_rstd(const float* ssq, int row0, int fq, float (&rs)[2][4]) {
; #pragma unroll
;     for (int ai = 0; ai < 2; ++ai)
; #pragma unroll
;         for (int m = 0; m < 4; ++m) {
;             const f32x4 v = *(const f32x4*)(ssq + (size_t)(row0 + ai * 128 + m * 16) * 16 + 4 * fq);
;             float s = (v[0] + v[1]) + (v[2] + v[3]);
;             s += __shfl_xor(s, 16); s += __shfl_xor(s, 32);
;             rs[ai][m] = rsqrtf(s * (1.0f / DM) + EPS);
;         }
; }
;     DI void operator()(const f32x4 (&acc)[2][2][4][2], const pg8::Unit& u, int wr, int wc, int fr, int fq) const {
;         const int row0 = u.pm * 256 + wr * 64 + fr, col0 = u.pn * 128 + wc * 32 + 8 * fq;
;         float rs[2][4]; row_rstd(ssq, row0, fq, rs);
; #pragma unroll
;         for (int ai = 0; ai < 2; ++ai)
; #pragma unroll
;             for (int m = 0; m < 4; ++m) {
;                 typedef float f32x2 __attribute__((ext_vector_type(2)));
;                 const float r = rs[ai][m]; const float r2s = r * r, rls = r * -1.44269504f; const f32x2 r2 = {r2s, r2s}, rl = {rls, rls};
;                 unsigned hw[4];
; #pragma unroll
;                 for (int q = 0; q < 4; ++q) {
;                     const f32x4 gq = acc[ai][0][m][q >> 1], uq = acc[ai][1][m][q >> 1];
;                     const f32x2 g2 = {gq[2 * (q & 1)], gq[2 * (q & 1) + 1]}, u2 = {uq[2 * (q & 1)], uq[2 * (q & 1) + 1]};
;                     const f32x2 t = g2 * rl; f32x2 e; e.x = __builtin_amdgcn_exp2f(t.x); e.y = __builtin_amdgcn_exp2f(t.y);
;                     const f32x2 d = e + 1.0f; f32x2 rc; rc.x = __builtin_amdgcn_rcpf(d.x); rc.y = __builtin_amdgcn_rcpf(d.y);
;                     const f32x2 hv = ((g2 * u2) * r2) * rc;
;                     hw[q] = pk2(hv.x, hv.y);
	v_mov_b32_e32 v130, v218
	v_mov_b32_e32 v131, v219
	v_mov_b32_e32 v132, v220
	v_mov_b32_e32 v133, v221
	v_mov_b32_e32 v146, v131
	v_mov_b32_e32 v147, v132
	v_mov_b32_e32 v131, v133
	v_pk_add_f32 v[146:147], v[146:147], v[130:131]
	v_lshlrev_b64 v[130:131], 6, v[150:151]
	v_lshl_add_u64 v[130:131], v[140:141], 0, v[130:131]
	s_waitcnt vmcnt(2)
	v_mov_b32_e32 v130, v222
	v_mov_b32_e32 v131, v223
	v_mov_b32_e32 v132, v224
	v_mov_b32_e32 v133, v225
	v_mov_b32_e32 v148, v131
	v_mov_b32_e32 v149, v132
	v_mov_b32_e32 v131, v133
	v_pk_add_f32 v[130:131], v[148:149], v[130:131]
	v_mov_b32_e32 v133, v146
	v_mov_b32_e32 v132, v130
	v_mov_b32_e32 v146, v131
	v_pk_add_f32 v[130:131], v[132:133], v[146:147]
	ds_bpermute_b32 v133, v186, v131
	ds_bpermute_b32 v132, v186, v130
	v_add_u32_e32 v148, 0xa0, v160
	v_ashrrev_i32_e32 v149, 31, v148
	s_waitcnt lgkmcnt(0)
	v_pk_add_f32 v[130:131], v[130:131], v[132:133]
	ds_bpermute_b32 v133, v163, v131
	ds_bpermute_b32 v132, v163, v130
	s_waitcnt lgkmcnt(0)
	v_pk_add_f32 v[130:131], v[130:131], v[132:133]
	s_nop 0
	v_pk_fma_f32 v[130:131], v[130:131], s[34:35], v[178:179] op_sel_hi:[1,0,0]
	s_nop 0
	v_mul_f32_e32 v132, 0x4b800000, v131
	v_cmp_gt_f32_e64 s[2:3], s25, v131
	v_cmp_gt_f32_e32 vcc, s25, v130
	s_nop 0
	v_cndmask_b32_e64 v131, v131, v132, s[2:3]
	v_rsq_f32_e32 v131, v131
	s_nop 0
	v_mul_f32_e32 v132, 0x45800000, v131
	v_cndmask_b32_e64 v153, v131, v132, s[2:3]
	v_mul_f32_e32 v131, 0x4b800000, v130
	v_cndmask_b32_e32 v130, v130, v131, vcc
	v_rsq_f32_e32 v130, v130
	s_nop 0
	v_mul_f32_e32 v131, 0x45800000, v130
	v_cndmask_b32_e32 v151, v130, v131, vcc
	v_lshlrev_b64 v[130:131], 6, v[148:149]
	v_lshl_add_u64 v[130:131], v[140:141], 0, v[130:131]
	v_accvgpr_write_b32 a0, v161
	v_accvgpr_write_b32 a1, v159
	v_accvgpr_write_b32 a2, v157
	v_accvgpr_write_b32 a3, v155
	v_accvgpr_write_b32 a4, v153
	v_accvgpr_write_b32 a5, v151
	s_mov_b32 s98, s58
	s_branch .Lrc_done_0
.Lrc_hit_0:
	v_add_u32_e32 v148, 0xa0, v160
	v_ashrrev_i32_e32 v149, 31, v148
	v_accvgpr_read_b32 v161, a0
	v_accvgpr_read_b32 v159, a1
	v_accvgpr_read_b32 v157, a2
	v_accvgpr_read_b32 v155, a3
	v_accvgpr_read_b32 v153, a4
	v_accvgpr_read_b32 v151, a5
.Lrc_done_0:
	s_waitcnt vmcnt(1)
	v_mov_b32_e32 v130, v226
	v_mov_b32_e32 v131, v227
	v_mov_b32_e32 v132, v228
	v_mov_b32_e32 v133, v229
	v_mov_b32_e32 v146, v131
	v_mov_b32_e32 v147, v132
	v_mov_b32_e32 v131, v133
	v_pk_add_f32 v[180:181], v[146:147], v[130:131]
	v_add_u32_e32 v146, 0xb0, v160
	v_ashrrev_i32_e32 v147, 31, v146
	v_lshlrev_b64 v[130:131], 6, v[146:147]
	v_lshl_add_u64 v[130:131], v[140:141], 0, v[130:131]
	s_waitcnt vmcnt(0)
	v_mov_b32_e32 v130, v230
	v_mov_b32_e32 v131, v231
	v_mov_b32_e32 v132, v232
	v_mov_b32_e32 v133, v233
	v_mov_b32_e32 v188, v131
	v_mov_b32_e32 v189, v132
	v_mov_b32_e32 v131, v133
	v_pk_add_f32 v[130:131], v[188:189], v[130:131]
	v_mov_b32_e32 v133, v180
	v_mov_b32_e32 v132, v130
	v_mov_b32_e32 v180, v131
	v_pk_add_f32 v[130:131], v[132:133], v[180:181]
	ds_bpermute_b32 v133, v186, v131
	ds_bpermute_b32 v132, v186, v130
	s_waitcnt lgkmcnt(0)
	v_pk_add_f32 v[130:131], v[130:131], v[132:133]
	ds_bpermute_b32 v133, v163, v131
	ds_bpermute_b32 v132, v163, v130
	v_ashrrev_i32_e32 v163, 31, v162
	s_waitcnt lgkmcnt(0)
	v_pk_add_f32 v[130:131], v[130:131], v[132:133]
	s_nop 0
	v_pk_fma_f32 v[130:131], v[130:131], s[34:35], v[178:179] op_sel_hi:[1,0,0]
	v_mul_f32_e32 v178, 0xbfb8aa3b, v161
	v_mul_f32_e32 v132, 0x4b800000, v131
	v_cmp_gt_f32_e64 s[2:3], s25, v131
	v_pk_mul_f32 v[180:181], v[126:127], v[178:179] op_sel_hi:[1,0]
	v_pk_mul_f32 v[126:127], v[128:129], v[178:179] op_sel_hi:[1,0]
	v_cndmask_b32_e64 v131, v131, v132, s[2:3]
	v_rsq_f32_e32 v131, v131
	v_cmp_gt_f32_e32 vcc, s25, v130
	v_exp_f32_e32 v180, v180
	v_exp_f32_e32 v181, v181
	v_mul_f32_e32 v132, 0x45800000, v131
	v_cndmask_b32_e64 v131, v131, v132, s[2:3]
	v_mul_f32_e32 v132, 0x4b800000, v130
	v_exp_f32_e32 v126, v126
	v_exp_f32_e32 v127, v127
	v_cndmask_b32_e32 v130, v130, v132, vcc
	v_rsq_f32_e32 v130, v130
	v_pk_add_f32 v[180:181], v[180:181], 1.0 op_sel_hi:[1,0]
	v_pk_add_f32 v[126:127], v[126:127], 1.0 op_sel_hi:[1,0]
	v_rcp_f32_e32 v180, v180
	v_rcp_f32_e32 v181, v181
	v_rcp_f32_e32 v126, v126
	v_rcp_f32_e32 v127, v127
	v_mul_f32_e32 v132, 0x45800000, v130
	v_cndmask_b32_e32 v130, v130, v132, vcc
	v_mul_f32_e32 v132, v161, v161
	v_pk_mul_f32 v[122:123], v[122:123], v[132:133] op_sel_hi:[1,0]
	v_pk_mul_f32 v[124:125], v[124:125], v[132:133] op_sel_hi:[1,0]
	v_pk_mul_f32 v[122:123], v[122:123], v[180:181]
	v_pk_mul_f32 v[124:125], v[124:125], v[126:127]
	v_cvt_pk_bf16_f32 v122, v122, v123
	v_cvt_pk_bf16_f32 v123, v124, v125
	v_pk_mul_f32 v[124:125], v[118:119], v[178:179] op_sel_hi:[1,0]
	v_pk_mul_f32 v[114:115], v[114:115], v[132:133] op_sel_hi:[1,0]
	v_exp_f32_e32 v124, v124
	v_exp_f32_e32 v125, v125
	v_pk_mul_f32 v[116:117], v[116:117], v[132:133] op_sel_hi:[1,0]
	s_andn2_b64 vcc, exec, s[40:41]
	v_pk_add_f32 v[124:125], v[124:125], 1.0 op_sel_hi:[1,0]
	s_nop 0
	v_rcp_f32_e32 v124, v124
	v_rcp_f32_e32 v125, v125
	s_nop 0
	v_pk_mul_f32 v[114:115], v[114:115], v[124:125]
	s_nop 0
	v_cvt_pk_bf16_f32 v124, v114, v115
	v_pk_mul_f32 v[114:115], v[120:121], v[178:179] op_sel_hi:[1,0]
	v_mul_f32_e32 v120, 0xbfb8aa3b, v159
	v_exp_f32_e32 v114, v114
	v_exp_f32_e32 v115, v115
	s_nop 0
	v_pk_add_f32 v[114:115], v[114:115], 1.0 op_sel_hi:[1,0]
	s_nop 0
	v_rcp_f32_e32 v114, v114
	v_rcp_f32_e32 v115, v115
	s_nop 0
	v_pk_mul_f32 v[114:115], v[116:117], v[114:115]
	s_nop 0
	v_cvt_pk_bf16_f32 v125, v114, v115
	v_mov_b64_e32 v[114:115], s[84:85]
	v_mad_i64_i32 v[118:119], s[2:3], v160, s27, v[114:115]
; DI unsigned pk2(float lo, float hi) { return pg8::cvt_pk_bf16(lo, hi); }
;     DI void operator()(const f32x4 (&acc)[2][2][4][2], const pg8::Unit& u, int wr, int wc, int fr, int fq) const {
;     ...
;             for (int m = 0; m < 4; ++m) {
;                 typedef float f32x2 __attribute__((ext_vector_type(2)));
;                 const float r = rs[ai][m]; const float r2s = r * r, rls = r * -1.44269504f; const f32x2 r2 = {r2s, r2s}, rl = {rls, rls};
;                 unsigned hw[4];
; #pragma unroll
;                 for (int q = 0; q < 4; ++q) {
;                     const f32x4 gq = acc[ai][0][m][q >> 1], uq = acc[ai][1][m][q >> 1];
;                     const f32x2 g2 = {gq[2 * (q & 1)], gq[2 * (q & 1) + 1]}, u2 = {uq[2 * (q & 1)], uq[2 * (q & 1) + 1]};
;                     const f32x2 t = g2 * rl; f32x2 e; e.x = __builtin_amdgcn_exp2f(t.x); e.y = __builtin_amdgcn_exp2f(t.y);
;                     const f32x2 d = e + 1.0f; f32x2 rc; rc.x = __builtin_amdgcn_rcpf(d.x); rc.y = __builtin_amdgcn_rcpf(d.y);
;                     const f32x2 hv = ((g2 * u2) * r2) * rc;
;                     hw[q] = pk2(hv.x, hv.y);
;                 }
;                 u32x4 w; w.x = hw[0]; w.y = hw[1]; w.z = hw[2]; w.w = hw[3];
;                 *(u32x4*)(H + (size_t)(row0 + ai * 128 + m * 16) * DFF + col0) = w;
	v_lshlrev_b64 v[116:117], 1, v[162:163]
	v_lshl_add_u64 v[118:119], v[118:119], 0, v[116:117]
	global_store_dwordx4 v[118:119], v[122:125], off
	v_mul_f32_e32 v118, v159, v159
	v_pk_mul_f32 v[106:107], v[106:107], v[118:119] op_sel_hi:[1,0]
	v_pk_mul_f32 v[122:123], v[110:111], v[120:121] op_sel_hi:[1,0]
	v_pk_mul_f32 v[110:111], v[112:113], v[120:121] op_sel_hi:[1,0]
	v_exp_f32_e32 v122, v122
	v_exp_f32_e32 v123, v123
	v_exp_f32_e32 v110, v110
	v_exp_f32_e32 v111, v111
	v_pk_mul_f32 v[108:109], v[108:109], v[118:119] op_sel_hi:[1,0]
	v_pk_add_f32 v[122:123], v[122:123], 1.0 op_sel_hi:[1,0]
	v_pk_mul_f32 v[98:99], v[98:99], v[118:119] op_sel_hi:[1,0]
	v_pk_add_f32 v[110:111], v[110:111], 1.0 op_sel_hi:[1,0]
	v_rcp_f32_e32 v122, v122
	v_rcp_f32_e32 v123, v123
	v_rcp_f32_e32 v110, v110
	v_rcp_f32_e32 v111, v111
	v_pk_mul_f32 v[100:101], v[100:101], v[118:119] op_sel_hi:[1,0]
	v_pk_mul_f32 v[106:107], v[106:107], v[122:123]
	v_pk_mul_f32 v[108:109], v[108:109], v[110:111]
	v_cvt_pk_bf16_f32 v106, v106, v107
	v_cvt_pk_bf16_f32 v107, v108, v109
	v_pk_mul_f32 v[108:109], v[102:103], v[120:121] op_sel_hi:[1,0]
	s_nop 0
	v_exp_f32_e32 v108, v108
	v_exp_f32_e32 v109, v109
	s_nop 0
	v_pk_add_f32 v[108:109], v[108:109], 1.0 op_sel_hi:[1,0]
	s_nop 0
	v_rcp_f32_e32 v108, v108
	v_rcp_f32_e32 v109, v109
	s_nop 0
	v_pk_mul_f32 v[98:99], v[98:99], v[108:109]
	s_nop 0
	v_cvt_pk_bf16_f32 v108, v98, v99
	v_pk_mul_f32 v[98:99], v[104:105], v[120:121] op_sel_hi:[1,0]
	s_nop 0
	v_exp_f32_e32 v98, v98
	v_exp_f32_e32 v99, v99
	s_nop 0
	v_pk_add_f32 v[98:99], v[98:99], 1.0 op_sel_hi:[1,0]
	s_nop 0
	v_rcp_f32_e32 v98, v98
	v_rcp_f32_e32 v99, v99
	s_nop 0
	v_pk_mul_f32 v[98:99], v[100:101], v[98:99]
	v_mul_f32_e32 v100, 0xbfb8aa3b, v157
	v_pk_mul_f32 v[102:103], v[94:95], v[100:101] op_sel_hi:[1,0]
	v_pk_mul_f32 v[94:95], v[96:97], v[100:101] op_sel_hi:[1,0]
	v_exp_f32_e32 v102, v102
	v_exp_f32_e32 v103, v103
	v_exp_f32_e32 v94, v94
	v_exp_f32_e32 v95, v95
	v_cvt_pk_bf16_f32 v109, v98, v99
	v_pk_add_f32 v[102:103], v[102:103], 1.0 op_sel_hi:[1,0]
	v_mad_i64_i32 v[98:99], s[2:3], v158, s27, v[114:115]
	v_pk_add_f32 v[94:95], v[94:95], 1.0 op_sel_hi:[1,0]
	v_rcp_f32_e32 v102, v102
	v_rcp_f32_e32 v103, v103
	v_rcp_f32_e32 v94, v94
	v_rcp_f32_e32 v95, v95
	v_lshl_add_u64 v[98:99], v[98:99], 0, v[116:117]
	global_store_dwordx4 v[98:99], v[106:109], off
	v_mul_f32_e32 v98, v157, v157
	v_pk_mul_f32 v[90:91], v[90:91], v[98:99] op_sel_hi:[1,0]
	v_pk_mul_f32 v[92:93], v[92:93], v[98:99] op_sel_hi:[1,0]
	v_pk_mul_f32 v[90:91], v[90:91], v[102:103]
	v_pk_mul_f32 v[92:93], v[92:93], v[94:95]
	v_cvt_pk_bf16_f32 v90, v90, v91
	v_cvt_pk_bf16_f32 v91, v92, v93
	v_pk_mul_f32 v[92:93], v[86:87], v[100:101] op_sel_hi:[1,0]
	v_pk_mul_f32 v[82:83], v[82:83], v[98:99] op_sel_hi:[1,0]
	v_exp_f32_e32 v92, v92
	v_exp_f32_e32 v93, v93
	v_pk_mul_f32 v[84:85], v[84:85], v[98:99] op_sel_hi:[1,0]
	v_pk_add_f32 v[92:93], v[92:93], 1.0 op_sel_hi:[1,0]
	s_nop 0
	v_rcp_f32_e32 v92, v92
	v_rcp_f32_e32 v93, v93
	s_nop 0
	v_pk_mul_f32 v[82:83], v[82:83], v[92:93]
	s_nop 0
	v_cvt_pk_bf16_f32 v92, v82, v83
	v_pk_mul_f32 v[82:83], v[88:89], v[100:101] op_sel_hi:[1,0]
	s_nop 0
	v_exp_f32_e32 v82, v82
	v_exp_f32_e32 v83, v83
	s_nop 0
	v_pk_add_f32 v[82:83], v[82:83], 1.0 op_sel_hi:[1,0]
	s_nop 0
	v_rcp_f32_e32 v82, v82
	v_rcp_f32_e32 v83, v83
	s_nop 0
	v_pk_mul_f32 v[82:83], v[84:85], v[82:83]
	v_mul_f32_e32 v84, 0xbfb8aa3b, v155
	v_pk_mul_f32 v[86:87], v[78:79], v[84:85] op_sel_hi:[1,0]
	v_pk_mul_f32 v[78:79], v[80:81], v[84:85] op_sel_hi:[1,0]
	v_exp_f32_e32 v86, v86
	v_exp_f32_e32 v87, v87
	v_exp_f32_e32 v78, v78
	v_exp_f32_e32 v79, v79
	v_cvt_pk_bf16_f32 v93, v82, v83
	v_pk_add_f32 v[86:87], v[86:87], 1.0 op_sel_hi:[1,0]
	v_mad_i64_i32 v[82:83], s[2:3], v156, s27, v[114:115]
	v_pk_add_f32 v[78:79], v[78:79], 1.0 op_sel_hi:[1,0]
	v_rcp_f32_e32 v86, v86
	v_rcp_f32_e32 v87, v87
	v_rcp_f32_e32 v78, v78
	v_rcp_f32_e32 v79, v79
	v_lshl_add_u64 v[82:83], v[82:83], 0, v[116:117]
	global_store_dwordx4 v[82:83], v[90:93], off
	v_mul_f32_e32 v82, v155, v155
	v_pk_mul_f32 v[74:75], v[74:75], v[82:83] op_sel_hi:[1,0]
	v_pk_mul_f32 v[76:77], v[76:77], v[82:83] op_sel_hi:[1,0]
	v_pk_mul_f32 v[74:75], v[74:75], v[86:87]
	v_pk_mul_f32 v[76:77], v[76:77], v[78:79]
	v_cvt_pk_bf16_f32 v74, v74, v75
	v_cvt_pk_bf16_f32 v75, v76, v77
	v_pk_mul_f32 v[76:77], v[70:71], v[84:85] op_sel_hi:[1,0]
	v_pk_mul_f32 v[66:67], v[66:67], v[82:83] op_sel_hi:[1,0]
	v_exp_f32_e32 v76, v76
	v_exp_f32_e32 v77, v77
	v_pk_mul_f32 v[68:69], v[68:69], v[82:83] op_sel_hi:[1,0]
	v_pk_add_f32 v[76:77], v[76:77], 1.0 op_sel_hi:[1,0]
	s_nop 0
	v_rcp_f32_e32 v76, v76
	v_rcp_f32_e32 v77, v77
	s_nop 0
	v_pk_mul_f32 v[66:67], v[66:67], v[76:77]
	s_nop 0
	v_cvt_pk_bf16_f32 v76, v66, v67
	v_pk_mul_f32 v[66:67], v[72:73], v[84:85] op_sel_hi:[1,0]
	s_nop 0
	v_exp_f32_e32 v66, v66
	v_exp_f32_e32 v67, v67
	s_nop 0
	v_pk_add_f32 v[66:67], v[66:67], 1.0 op_sel_hi:[1,0]
	s_nop 0
	v_rcp_f32_e32 v66, v66
	v_rcp_f32_e32 v67, v67
	s_nop 0
	v_pk_mul_f32 v[66:67], v[68:69], v[66:67]
	v_mul_f32_e32 v68, 0xbfb8aa3b, v153
	v_pk_mul_f32 v[70:71], v[62:63], v[68:69] op_sel_hi:[1,0]
	v_pk_mul_f32 v[62:63], v[64:65], v[68:69] op_sel_hi:[1,0]
	v_exp_f32_e32 v70, v70
	v_exp_f32_e32 v71, v71
	v_exp_f32_e32 v62, v62
	v_exp_f32_e32 v63, v63
	v_cvt_pk_bf16_f32 v77, v66, v67
	v_pk_add_f32 v[70:71], v[70:71], 1.0 op_sel_hi:[1,0]
	v_mad_i64_i32 v[66:67], s[2:3], v154, s27, v[114:115]
	v_pk_add_f32 v[62:63], v[62:63], 1.0 op_sel_hi:[1,0]
	v_rcp_f32_e32 v70, v70
	v_rcp_f32_e32 v71, v71
	v_rcp_f32_e32 v62, v62
	v_rcp_f32_e32 v63, v63
	v_lshl_add_u64 v[66:67], v[66:67], 0, v[116:117]
; DI unsigned pk2(float lo, float hi) { return pg8::cvt_pk_bf16(lo, hi); }
;     DI void operator()(const f32x4 (&acc)[2][2][4][2], const pg8::Unit& u, int wr, int wc, int fr, int fq) const {
;     ...
;             for (int m = 0; m < 4; ++m) {
;                 typedef float f32x2 __attribute__((ext_vector_type(2)));
;                 const float r = rs[ai][m]; const float r2s = r * r, rls = r * -1.44269504f; const f32x2 r2 = {r2s, r2s}, rl = {rls, rls};
;                 unsigned hw[4];
; #pragma unroll
;                 for (int q = 0; q < 4; ++q) {
;                     const f32x4 gq = acc[ai][0][m][q >> 1], uq = acc[ai][1][m][q >> 1];
;                     const f32x2 g2 = {gq[2 * (q & 1)], gq[2 * (q & 1) + 1]}, u2 = {uq[2 * (q & 1)], uq[2 * (q & 1) + 1]};
;                     const f32x2 t = g2 * rl; f32x2 e; e.x = __builtin_amdgcn_exp2f(t.x); e.y = __builtin_amdgcn_exp2f(t.y);
;                     const f32x2 d = e + 1.0f; f32x2 rc; rc.x = __builtin_amdgcn_rcpf(d.x); rc.y = __builtin_amdgcn_rcpf(d.y);
;                     const f32x2 hv = ((g2 * u2) * r2) * rc;
;                     hw[q] = pk2(hv.x, hv.y);
;                 }
;                 u32x4 w; w.x = hw[0]; w.y = hw[1]; w.z = hw[2]; w.w = hw[3];
;                 *(u32x4*)(H + (size_t)(row0 + ai * 128 + m * 16) * DFF + col0) = w;
	global_store_dwordx4 v[66:67], v[74:77], off
	v_mul_f32_e32 v66, v153, v153
	v_pk_mul_f32 v[58:59], v[58:59], v[66:67] op_sel_hi:[1,0]
	v_pk_mul_f32 v[60:61], v[60:61], v[66:67] op_sel_hi:[1,0]
	v_pk_mul_f32 v[58:59], v[58:59], v[70:71]
	v_pk_mul_f32 v[60:61], v[60:61], v[62:63]
	v_cvt_pk_bf16_f32 v58, v58, v59
	v_cvt_pk_bf16_f32 v59, v60, v61
	v_pk_mul_f32 v[60:61], v[54:55], v[68:69] op_sel_hi:[1,0]
	v_pk_mul_f32 v[50:51], v[50:51], v[66:67] op_sel_hi:[1,0]
	v_exp_f32_e32 v60, v60
	v_exp_f32_e32 v61, v61
	v_pk_mul_f32 v[52:53], v[52:53], v[66:67] op_sel_hi:[1,0]
	v_pk_add_f32 v[60:61], v[60:61], 1.0 op_sel_hi:[1,0]
	s_nop 0
	v_rcp_f32_e32 v60, v60
	v_rcp_f32_e32 v61, v61
	s_nop 0
	v_pk_mul_f32 v[50:51], v[50:51], v[60:61]
	s_nop 0
	v_cvt_pk_bf16_f32 v60, v50, v51
	v_pk_mul_f32 v[50:51], v[56:57], v[68:69] op_sel_hi:[1,0]
	s_nop 0
	v_exp_f32_e32 v50, v50
	v_exp_f32_e32 v51, v51
	s_nop 0
	v_pk_add_f32 v[50:51], v[50:51], 1.0 op_sel_hi:[1,0]
	s_nop 0
	v_rcp_f32_e32 v50, v50
	v_rcp_f32_e32 v51, v51
	s_nop 0
	v_pk_mul_f32 v[50:51], v[52:53], v[50:51]
	v_mul_f32_e32 v52, 0xbfb8aa3b, v151
	v_pk_mul_f32 v[54:55], v[46:47], v[52:53] op_sel_hi:[1,0]
	v_pk_mul_f32 v[46:47], v[48:49], v[52:53] op_sel_hi:[1,0]
	v_exp_f32_e32 v54, v54
	v_exp_f32_e32 v55, v55
	v_exp_f32_e32 v46, v46
	v_exp_f32_e32 v47, v47
	v_cvt_pk_bf16_f32 v61, v50, v51
	v_pk_add_f32 v[54:55], v[54:55], 1.0 op_sel_hi:[1,0]
	v_mad_i64_i32 v[50:51], s[2:3], v152, s27, v[114:115]
	v_pk_add_f32 v[46:47], v[46:47], 1.0 op_sel_hi:[1,0]
	v_rcp_f32_e32 v54, v54
	v_rcp_f32_e32 v55, v55
	v_rcp_f32_e32 v46, v46
	v_rcp_f32_e32 v47, v47
	v_lshl_add_u64 v[50:51], v[50:51], 0, v[116:117]
	global_store_dwordx4 v[50:51], v[58:61], off
	v_mul_f32_e32 v50, v151, v151
	v_pk_mul_f32 v[42:43], v[42:43], v[50:51] op_sel_hi:[1,0]
	v_pk_mul_f32 v[44:45], v[44:45], v[50:51] op_sel_hi:[1,0]
	v_pk_mul_f32 v[42:43], v[42:43], v[54:55]
	v_pk_mul_f32 v[44:45], v[44:45], v[46:47]
	v_cvt_pk_bf16_f32 v42, v42, v43
	v_cvt_pk_bf16_f32 v43, v44, v45
	v_pk_mul_f32 v[44:45], v[38:39], v[52:53] op_sel_hi:[1,0]
	v_pk_mul_f32 v[34:35], v[34:35], v[50:51] op_sel_hi:[1,0]
	v_exp_f32_e32 v44, v44
	v_exp_f32_e32 v45, v45
	v_pk_mul_f32 v[36:37], v[36:37], v[50:51] op_sel_hi:[1,0]
	v_pk_add_f32 v[44:45], v[44:45], 1.0 op_sel_hi:[1,0]
	s_nop 0
	v_rcp_f32_e32 v44, v44
	v_rcp_f32_e32 v45, v45
	s_nop 0
	v_pk_mul_f32 v[34:35], v[34:35], v[44:45]
	s_nop 0
	v_cvt_pk_bf16_f32 v44, v34, v35
	v_pk_mul_f32 v[34:35], v[40:41], v[52:53] op_sel_hi:[1,0]
	s_nop 0
	v_exp_f32_e32 v34, v34
	v_exp_f32_e32 v35, v35
	s_nop 0
	v_pk_add_f32 v[34:35], v[34:35], 1.0 op_sel_hi:[1,0]
	s_nop 0
	v_rcp_f32_e32 v34, v34
	v_rcp_f32_e32 v35, v35
	s_nop 0
	v_pk_mul_f32 v[34:35], v[36:37], v[34:35]
	v_mul_f32_e32 v36, 0xbfb8aa3b, v131
	v_pk_mul_f32 v[38:39], v[30:31], v[36:37] op_sel_hi:[1,0]
	v_pk_mul_f32 v[30:31], v[32:33], v[36:37] op_sel_hi:[1,0]
	v_exp_f32_e32 v38, v38
	v_exp_f32_e32 v39, v39
	v_exp_f32_e32 v30, v30
	v_exp_f32_e32 v31, v31
	v_cvt_pk_bf16_f32 v45, v34, v35
	v_pk_add_f32 v[38:39], v[38:39], 1.0 op_sel_hi:[1,0]
	v_mad_i64_i32 v[34:35], s[2:3], v150, s27, v[114:115]
	v_pk_add_f32 v[30:31], v[30:31], 1.0 op_sel_hi:[1,0]
	v_rcp_f32_e32 v38, v38
	v_rcp_f32_e32 v39, v39
	v_rcp_f32_e32 v30, v30
	v_rcp_f32_e32 v31, v31
	v_lshl_add_u64 v[34:35], v[34:35], 0, v[116:117]
	global_store_dwordx4 v[34:35], v[42:45], off
	v_mul_f32_e32 v34, v131, v131
	v_pk_mul_f32 v[26:27], v[26:27], v[34:35] op_sel_hi:[1,0]
	v_pk_mul_f32 v[28:29], v[28:29], v[34:35] op_sel_hi:[1,0]
	v_pk_mul_f32 v[26:27], v[26:27], v[38:39]
	v_pk_mul_f32 v[28:29], v[28:29], v[30:31]
	v_cvt_pk_bf16_f32 v26, v26, v27
	v_cvt_pk_bf16_f32 v27, v28, v29
	v_pk_mul_f32 v[28:29], v[22:23], v[36:37] op_sel_hi:[1,0]
	v_pk_mul_f32 v[18:19], v[18:19], v[34:35] op_sel_hi:[1,0]
	v_exp_f32_e32 v28, v28
	v_exp_f32_e32 v29, v29
	v_pk_mul_f32 v[20:21], v[20:21], v[34:35] op_sel_hi:[1,0]
	v_pk_add_f32 v[28:29], v[28:29], 1.0 op_sel_hi:[1,0]
	s_nop 0
	v_rcp_f32_e32 v28, v28
	v_rcp_f32_e32 v29, v29
	s_nop 0
	v_pk_mul_f32 v[18:19], v[18:19], v[28:29]
	s_nop 0
	v_cvt_pk_bf16_f32 v28, v18, v19
	v_pk_mul_f32 v[18:19], v[24:25], v[36:37] op_sel_hi:[1,0]
	s_nop 0
	v_exp_f32_e32 v18, v18
	v_exp_f32_e32 v19, v19
	s_nop 0
	v_pk_add_f32 v[18:19], v[18:19], 1.0 op_sel_hi:[1,0]
	s_nop 0
	v_rcp_f32_e32 v18, v18
	v_rcp_f32_e32 v19, v19
	s_nop 0
	v_pk_mul_f32 v[18:19], v[20:21], v[18:19]
	v_mul_f32_e32 v20, 0xbfb8aa3b, v130
	v_pk_mul_f32 v[22:23], v[14:15], v[20:21] op_sel_hi:[1,0]
	v_pk_mul_f32 v[14:15], v[16:17], v[20:21] op_sel_hi:[1,0]
	v_exp_f32_e32 v22, v22
	v_exp_f32_e32 v23, v23
	v_exp_f32_e32 v14, v14
	v_exp_f32_e32 v15, v15
	v_cvt_pk_bf16_f32 v29, v18, v19
	v_pk_add_f32 v[22:23], v[22:23], 1.0 op_sel_hi:[1,0]
	v_mad_i64_i32 v[18:19], s[2:3], v148, s27, v[114:115]
	v_pk_add_f32 v[14:15], v[14:15], 1.0 op_sel_hi:[1,0]
	v_rcp_f32_e32 v22, v22
	v_rcp_f32_e32 v23, v23
	v_rcp_f32_e32 v14, v14
	v_rcp_f32_e32 v15, v15
	v_lshl_add_u64 v[18:19], v[18:19], 0, v[116:117]
	global_store_dwordx4 v[18:19], v[26:29], off
	v_mul_f32_e32 v18, v130, v130
	v_pk_mul_f32 v[10:11], v[10:11], v[18:19] op_sel_hi:[1,0]
	v_pk_mul_f32 v[12:13], v[12:13], v[18:19] op_sel_hi:[1,0]
	v_pk_mul_f32 v[10:11], v[10:11], v[22:23]
	v_pk_mul_f32 v[12:13], v[12:13], v[14:15]
	v_cvt_pk_bf16_f32 v10, v10, v11
	v_cvt_pk_bf16_f32 v11, v12, v13
	v_pk_mul_f32 v[12:13], v[6:7], v[20:21] op_sel_hi:[1,0]
	v_pk_mul_f32 v[2:3], v[2:3], v[18:19] op_sel_hi:[1,0]
	v_exp_f32_e32 v12, v12
	v_exp_f32_e32 v13, v13
	v_pk_mul_f32 v[4:5], v[4:5], v[18:19] op_sel_hi:[1,0]
	v_pk_add_f32 v[12:13], v[12:13], 1.0 op_sel_hi:[1,0]
	s_nop 0
	v_rcp_f32_e32 v12, v12
	v_rcp_f32_e32 v13, v13
	s_nop 0
	v_pk_mul_f32 v[2:3], v[2:3], v[12:13]
	s_nop 0
	v_cvt_pk_bf16_f32 v12, v2, v3
	v_pk_mul_f32 v[2:3], v[8:9], v[20:21] op_sel_hi:[1,0]
	s_nop 0
	v_exp_f32_e32 v2, v2
	v_exp_f32_e32 v3, v3
	s_nop 0
	v_pk_add_f32 v[2:3], v[2:3], 1.0 op_sel_hi:[1,0]
	s_nop 0
	v_rcp_f32_e32 v2, v2
	v_rcp_f32_e32 v3, v3
	s_nop 0
	v_pk_mul_f32 v[2:3], v[4:5], v[2:3]
	s_nop 0
	v_cvt_pk_bf16_f32 v13, v2, v3
	v_mad_i64_i32 v[2:3], s[2:3], v146, s27, v[114:115]
	v_lshl_add_u64 v[2:3], v[2:3], 0, v[116:117]
	s_mov_b64 s[2:3], -1
	global_store_dwordx4 v[2:3], v[10:13], off
	s_cbranch_vccnz .LBB0_162
	s_andn2_b64 vcc, exec, s[38:39]
	s_cbranch_vccnz .LBB0_161
	s_barrier
	s_branch .LBB0_161

; #define PG8_STAGE(bufoff, gbase, voff) do { _Pragma("unroll") for (int _i = 0; _i < 2; ++_i) \
;         __builtin_amdgcn_global_load_lds((const unsigned*)((const char*)(gbase) + (voff)[_i]), (PG8_LAS unsigned*)(lds + (bufoff) + ldsw + _i * 8192), 16, 0, 0); } while (0)
; #define PG8_WAIT_V(n) asm volatile("s_waitcnt vmcnt(" #n ")" ::: "memory")
; #define PG8_BAR __builtin_amdgcn_s_barrier()
; template <class Epi, class Sched, bool ALIGN_EPI = false, bool SP2 = false>
; __device__ __forceinline__ void gemm_phase(PG8_LAS unsigned char* lds, const Gemm g, const Sched& S, const Epi& E) {
;     ...
;     for (int i = 0; i < 2; ++i) { int R, C; stage_rc(tid * 16 + i * 8192, R, C); const int Rb = Epi::PERM ? ((R & ~31) + perm32(R & 31)) : R;
;         voffA[i] = (unsigned)(R * K + C) * 2u; voffB[i] = (unsigned)(Rb * K + C) * 2u; }
;     const size_t kstep = (size_t)(BK * 2);
;     const size_t hstep = (size_t)HALF * K * 2;
;     const size_t tstep = 2 * hstep;
;     const unsigned ldsw = (unsigned)wid * 1024u;
;     const int aoff = lds_byte(wr * 64 + fr, fq * 8), boff = lds_byte(wc * 32 + fr, fq * 8);
;     ...
;     Unit cur, nxt; int ui = 0;
;     if (!S.next(0, cur)) return;
;     f32x4 acc[2][2][4][2];
; #pragma unroll
;     for (int a = 0; a < 2; ++a)
; #pragma unroll
;         for (int b = 0; b < 2; ++b)
; #pragma unroll
;             for (int m = 0; m < 4; ++m)
; #pragma unroll
;                 for (int n = 0; n < 2; ++n) acc[a][b][m][n] = (f32x4){0.f, 0.f, 0.f, 0.f};
;     bf16x8 At[4][2], B0[2][2], B1[2][2];
;     const char* cA = (const char*)g.A + (size_t)cur.pm * tstep; const char* cB = (const char*)g.Bt + (size_t)cur.pn * tstep;
;     S.a_ready(cur);
;     if constexpr (SP2) {
;         PG8_STAGE(PG8_SB(0, 0), cB, voffB); PG8_STAGE(PG8_SB(0, 1), cB + hstep, voffB); PG8_STAGE(PG8_SA(0, 0), cA, voffA); PG8_STAGE(PG8_SA(0, 1), cA + hstep, voffA);
;         if (wr == 1) PG8_BAR;
;         PG8_WAIT_V(2); PG8_BAR;
;         PG8_STAGE(PG8_SB(1, 0), cB + kstep, voffB); PG8_STAGE(PG8_SA(1, 0), cA + kstep, voffA); PG8_STAGE(PG8_SB(1, 1), cB + hstep + kstep, voffB);
;         PG8_WAIT_V(6); PG8_BAR;
.LBB0_1116:
	v_readlane_b32 s50, v245, 24
	s_lshl_b32 s14, s14, 5
	v_mov_b32_e32 v139, v1
	v_readlane_b32 s51, v245, 25
	s_and_b32 s23, s14, 0x60
	s_add_i32 m0, s30, 0x18000
	v_lshl_add_u64 v[2:3], v[2:3], 0, s[20:21]
	s_waitcnt vmcnt(0)
	v_lshl_add_u64 v[14:15], s[50:51], 0, v[138:139]
	v_mov_b32_e32 v137, v1
	s_lshl_b32 s22, s3, 13
	s_lshl_b32 s38, s23, 7
	s_waitcnt vmcnt(2)
	s_barrier
	global_load_lds_dwordx4 v[2:3], off
	v_lshl_add_u64 v[2:3], v[4:5], 0, s[20:21]
	s_add_i32 m0, s30, 0x1a000
	s_add_i32 s54, s30, 0x8000
	s_add_i32 s55, s30, 0xa000
	v_lshl_add_u64 v[16:17], s[50:51], 0, v[136:137]
	global_load_lds_dwordx4 v[2:3], off
	v_lshl_add_u64 v[2:3], v[14:15], 0, s[20:21]
	s_mov_b32 m0, s54
	s_add_u32 s14, s12, 0x40080
	global_load_lds_dwordx4 v[2:3], off
	v_lshl_add_u64 v[2:3], v[16:17], 0, s[20:21]
	s_mov_b32 m0, s55
	s_addc_u32 s15, s13, 0
	global_load_lds_dwordx4 v[2:3], off
	s_add_i32 m0, s30, 0x1c000
	v_lshl_add_u64 v[2:3], s[14:15], 0, v[0:1]
	global_load_lds_dwordx4 v[2:3], off
	v_lshl_add_u64 v[2:3], s[14:15], 0, v[134:135]
	s_add_i32 m0, s30, 0x1e000
	v_bfe_u32 v4, v7, 4, 2
	global_load_lds_dwordx4 v[2:3], off
	v_and_b32_e32 v3, 15, v7
	v_lshlrev_b32_e32 v2, 4, v4
	v_lshlrev_b32_e32 v5, 2, v7
	v_lshl_or_b32 v182, s3, 6, v3
	v_lshl_or_b32 v3, v3, 6, v2
	v_and_b32_e32 v5, 32, v5
	v_bitop3_b32 v7, v3, s22, v5 bitop3:0xde
	v_bitop3_b32 v183, v3, s38, v5 bitop3:0xde
	v_mov_b32_e32 v3, v1
	v_lshl_add_u64 v[140:141], s[88:89], 0, v[2:3]
	v_lshlrev_b32_e32 v2, 14, v11
	v_and_b32_e32 v2, 0xffff8000, v2
	v_lshl_add_u32 v2, v10, 11, v2
	v_and_b32_e32 v3, 1, v11
	v_lshl_or_b32 v2, v3, 6, v2
	v_lshl_add_u32 v142, v12, 1, v2
	v_lshlrev_b32_e32 v2, 14, v6
	v_and_b32_e32 v2, 0xffff8000, v2
	s_waitcnt vmcnt(6)
	s_cmpk_lt_u32 s2, 0x100
	v_lshl_add_u32 v2, v8, 11, v2
	v_and_b32_e32 v3, 1, v6
	v_readlane_b32 s2, v245, 22
	v_lshl_or_b32 v2, v3, 6, v2
	v_readlane_b32 s3, v245, 23
	s_cselect_b64 s[44:45], -1, 0
	v_lshl_or_b32 v184, v4, 3, s23
	v_mov_b32_e32 v143, v1
	v_lshl_add_u32 v144, v9, 1, v2
	v_mov_b32_e32 v145, v1
	s_mov_b32 s56, 0
	v_add_u32_e32 v185, 0, v7
	v_readlane_b32 s57, v245, 19
	s_mov_b32 s58, s2
	s_mov_b64 s[2:3], s[50:51]
	s_barrier
	s_mov_b32 s98, -1
	s_branch .LBB0_1119

; DI unsigned pk2(float lo, float hi) { return pg8::cvt_pk_bf16(lo, hi); }
; DI void row_rstd(const float* ssq, int row0, int fq, float (&rs)[2][4]) {
; #pragma unroll
;     for (int ai = 0; ai < 2; ++ai)
; #pragma unroll
;         for (int m = 0; m < 4; ++m) {
;             const f32x4 v = *(const f32x4*)(ssq + (size_t)(row0 + ai * 128 + m * 16) * 16 + 4 * fq);
;             float s = (v[0] + v[1]) + (v[2] + v[3]);
;             s += __shfl_xor(s, 16); s += __shfl_xor(s, 32);
;             rs[ai][m] = rsqrtf(s * (1.0f / DM) + EPS);
;         }
; }
;     DI void operator()(const f32x4 (&acc)[2][2][4][2], const pg8::Unit& u, int wr, int wc, int fr, int fq) const {
;         const int row0 = u.pm * 256 + wr * 64 + fr, col0 = u.pn * 128 + wc * 32 + 8 * fq;
;         float rs[2][4]; row_rstd(ssq, row0, fq, rs);
; #pragma unroll
;         for (int ai = 0; ai < 2; ++ai)
; #pragma unroll
;             for (int m = 0; m < 4; ++m) {
;                 typedef float f32x2 __attribute__((ext_vector_type(2)));
;                 const float r = rs[ai][m]; const float r2s = r * r, rls = r * -1.44269504f; const f32x2 r2 = {r2s, r2s}, rl = {rls, rls};
;                 unsigned hw[4];
; #pragma unroll
;                 for (int q = 0; q < 4; ++q) {
;                     const f32x4 gq = acc[ai][0][m][q >> 1], uq = acc[ai][1][m][q >> 1];
;                     const f32x2 g2 = {gq[2 * (q & 1)], gq[2 * (q & 1) + 1]}, u2 = {uq[2 * (q & 1)], uq[2 * (q & 1) + 1]};
;                     const f32x2 t = g2 * rl; f32x2 e; e.x = __builtin_amdgcn_exp2f(t.x); e.y = __builtin_amdgcn_exp2f(t.y);
;                     const f32x2 d = e + 1.0f; f32x2 rc; rc.x = __builtin_amdgcn_rcpf(d.x); rc.y = __builtin_amdgcn_rcpf(d.y);
;                     const f32x2 hv = ((g2 * u2) * r2) * rc;
;                     hw[q] = pk2(hv.x, hv.y);
;                 }
;                 u32x4 w; w.x = hw[0]; w.y = hw[1]; w.z = hw[2]; w.w = hw[3];
;                 *(u32x4*)(H + (size_t)(row0 + ai * 128 + m * 16) * DFF + col0) = w;
.Lrc_done_1:
	s_waitcnt vmcnt(1)
	v_mov_b32_e32 v130, v226
	v_mov_b32_e32 v131, v227
	v_mov_b32_e32 v132, v228
	v_mov_b32_e32 v133, v229
	v_mov_b32_e32 v146, v131
	v_mov_b32_e32 v147, v132
	v_mov_b32_e32 v131, v133
	v_pk_add_f32 v[180:181], v[146:147], v[130:131]
	v_add_u32_e32 v146, 0xb0, v160
	v_ashrrev_i32_e32 v147, 31, v146
	v_lshlrev_b64 v[130:131], 6, v[146:147]
	v_lshl_add_u64 v[130:131], v[140:141], 0, v[130:131]
	s_waitcnt vmcnt(0)
	v_mov_b32_e32 v130, v230
	v_mov_b32_e32 v131, v231
	v_mov_b32_e32 v132, v232
	v_mov_b32_e32 v133, v233
	v_mov_b32_e32 v188, v131
	v_mov_b32_e32 v189, v132
	v_mov_b32_e32 v131, v133
	v_pk_add_f32 v[130:131], v[188:189], v[130:131]
	v_mov_b32_e32 v133, v180
	v_mov_b32_e32 v132, v130
	v_mov_b32_e32 v180, v131
	v_pk_add_f32 v[130:131], v[132:133], v[180:181]
	ds_bpermute_b32 v133, v186, v131
	ds_bpermute_b32 v132, v186, v130
	s_waitcnt lgkmcnt(0)
	v_pk_add_f32 v[130:131], v[130:131], v[132:133]
	ds_bpermute_b32 v133, v163, v131
	ds_bpermute_b32 v132, v163, v130
	v_ashrrev_i32_e32 v163, 31, v162
	s_waitcnt lgkmcnt(0)
	v_pk_add_f32 v[130:131], v[130:131], v[132:133]
	s_nop 0
	v_pk_fma_f32 v[130:131], v[130:131], s[34:35], v[178:179] op_sel_hi:[1,0,0]
	v_mul_f32_e32 v178, 0xbfb8aa3b, v161
	v_mul_f32_e32 v132, 0x4b800000, v131
	v_cmp_gt_f32_e64 s[2:3], s25, v131
	v_pk_mul_f32 v[180:181], v[126:127], v[178:179] op_sel_hi:[1,0]
	v_pk_mul_f32 v[126:127], v[128:129], v[178:179] op_sel_hi:[1,0]
	v_cndmask_b32_e64 v131, v131, v132, s[2:3]
	v_rsq_f32_e32 v131, v131
	v_cmp_gt_f32_e32 vcc, s25, v130
	v_exp_f32_e32 v180, v180
	v_exp_f32_e32 v181, v181
	v_mul_f32_e32 v132, 0x45800000, v131
	v_cndmask_b32_e64 v131, v131, v132, s[2:3]
	v_mul_f32_e32 v132, 0x4b800000, v130
	v_exp_f32_e32 v126, v126
	v_exp_f32_e32 v127, v127
	v_cndmask_b32_e32 v130, v130, v132, vcc
	v_rsq_f32_e32 v130, v130
	v_pk_add_f32 v[180:181], v[180:181], 1.0 op_sel_hi:[1,0]
	v_pk_add_f32 v[126:127], v[126:127], 1.0 op_sel_hi:[1,0]
	v_rcp_f32_e32 v180, v180
	v_rcp_f32_e32 v181, v181
	v_rcp_f32_e32 v126, v126
	v_rcp_f32_e32 v127, v127
	v_mul_f32_e32 v132, 0x45800000, v130
	v_cndmask_b32_e32 v130, v130, v132, vcc
	v_mul_f32_e32 v132, v161, v161
	v_pk_mul_f32 v[122:123], v[122:123], v[132:133] op_sel_hi:[1,0]
	v_pk_mul_f32 v[124:125], v[124:125], v[132:133] op_sel_hi:[1,0]
	v_pk_mul_f32 v[122:123], v[122:123], v[180:181]
	v_pk_mul_f32 v[124:125], v[124:125], v[126:127]
	v_cvt_pk_bf16_f32 v122, v122, v123
	v_cvt_pk_bf16_f32 v123, v124, v125
	v_pk_mul_f32 v[124:125], v[118:119], v[178:179] op_sel_hi:[1,0]
	v_pk_mul_f32 v[114:115], v[114:115], v[132:133] op_sel_hi:[1,0]
	v_exp_f32_e32 v124, v124
	v_exp_f32_e32 v125, v125
	v_pk_mul_f32 v[116:117], v[116:117], v[132:133] op_sel_hi:[1,0]
	s_andn2_b64 vcc, exec, s[38:39]
	v_pk_add_f32 v[124:125], v[124:125], 1.0 op_sel_hi:[1,0]
	s_nop 0
	v_rcp_f32_e32 v124, v124
	v_rcp_f32_e32 v125, v125
	s_nop 0
	v_pk_mul_f32 v[114:115], v[114:115], v[124:125]
	s_nop 0
	v_cvt_pk_bf16_f32 v124, v114, v115
	v_pk_mul_f32 v[114:115], v[120:121], v[178:179] op_sel_hi:[1,0]
	v_mul_f32_e32 v120, 0xbfb8aa3b, v159
	v_exp_f32_e32 v114, v114
	v_exp_f32_e32 v115, v115
	s_nop 0
	v_pk_add_f32 v[114:115], v[114:115], 1.0 op_sel_hi:[1,0]
	s_nop 0
	v_rcp_f32_e32 v114, v114
	v_rcp_f32_e32 v115, v115
	s_nop 0
	v_pk_mul_f32 v[114:115], v[116:117], v[114:115]
	s_nop 0
	v_cvt_pk_bf16_f32 v125, v114, v115
	v_mov_b64_e32 v[114:115], s[84:85]
	v_mad_i64_i32 v[118:119], s[2:3], v160, s27, v[114:115]
	v_lshlrev_b64 v[116:117], 1, v[162:163]
	v_lshl_add_u64 v[118:119], v[118:119], 0, v[116:117]
	global_store_dwordx4 v[118:119], v[122:125], off
	v_mul_f32_e32 v118, v159, v159
	v_pk_mul_f32 v[106:107], v[106:107], v[118:119] op_sel_hi:[1,0]
	v_pk_mul_f32 v[122:123], v[110:111], v[120:121] op_sel_hi:[1,0]
	v_pk_mul_f32 v[110:111], v[112:113], v[120:121] op_sel_hi:[1,0]
	v_exp_f32_e32 v122, v122
	v_exp_f32_e32 v123, v123
	v_exp_f32_e32 v110, v110
	v_exp_f32_e32 v111, v111
	v_pk_mul_f32 v[108:109], v[108:109], v[118:119] op_sel_hi:[1,0]
	v_pk_add_f32 v[122:123], v[122:123], 1.0 op_sel_hi:[1,0]
	v_pk_mul_f32 v[98:99], v[98:99], v[118:119] op_sel_hi:[1,0]
	v_pk_add_f32 v[110:111], v[110:111], 1.0 op_sel_hi:[1,0]
	v_rcp_f32_e32 v122, v122
	v_rcp_f32_e32 v123, v123
	v_rcp_f32_e32 v110, v110
	v_rcp_f32_e32 v111, v111
	v_pk_mul_f32 v[100:101], v[100:101], v[118:119] op_sel_hi:[1,0]
	v_pk_mul_f32 v[106:107], v[106:107], v[122:123]
	v_pk_mul_f32 v[108:109], v[108:109], v[110:111]
	v_cvt_pk_bf16_f32 v106, v106, v107
	v_cvt_pk_bf16_f32 v107, v108, v109
	v_pk_mul_f32 v[108:109], v[102:103], v[120:121] op_sel_hi:[1,0]
	s_nop 0
	v_exp_f32_e32 v108, v108
	v_exp_f32_e32 v109, v109
	s_nop 0
	v_pk_add_f32 v[108:109], v[108:109], 1.0 op_sel_hi:[1,0]
	s_nop 0
	v_rcp_f32_e32 v108, v108
	v_rcp_f32_e32 v109, v109
	s_nop 0
	v_pk_mul_f32 v[98:99], v[98:99], v[108:109]
	s_nop 0
	v_cvt_pk_bf16_f32 v108, v98, v99
	v_pk_mul_f32 v[98:99], v[104:105], v[120:121] op_sel_hi:[1,0]
	s_nop 0
	v_exp_f32_e32 v98, v98
	v_exp_f32_e32 v99, v99
	s_nop 0
	v_pk_add_f32 v[98:99], v[98:99], 1.0 op_sel_hi:[1,0]
	s_nop 0
	v_rcp_f32_e32 v98, v98
	v_rcp_f32_e32 v99, v99
	s_nop 0
	v_pk_mul_f32 v[98:99], v[100:101], v[98:99]
	v_mul_f32_e32 v100, 0xbfb8aa3b, v157
	v_pk_mul_f32 v[102:103], v[94:95], v[100:101] op_sel_hi:[1,0]
	v_pk_mul_f32 v[94:95], v[96:97], v[100:101] op_sel_hi:[1,0]
	v_exp_f32_e32 v102, v102
	v_exp_f32_e32 v103, v103
	v_exp_f32_e32 v94, v94
	v_exp_f32_e32 v95, v95
	v_cvt_pk_bf16_f32 v109, v98, v99
	v_pk_add_f32 v[102:103], v[102:103], 1.0 op_sel_hi:[1,0]
	v_mad_i64_i32 v[98:99], s[2:3], v158, s27, v[114:115]
	v_pk_add_f32 v[94:95], v[94:95], 1.0 op_sel_hi:[1,0]
	v_rcp_f32_e32 v102, v102
; DI unsigned pk2(float lo, float hi) { return pg8::cvt_pk_bf16(lo, hi); }
;     DI void operator()(const f32x4 (&acc)[2][2][4][2], const pg8::Unit& u, int wr, int wc, int fr, int fq) const {
;     ...
;             for (int m = 0; m < 4; ++m) {
;                 typedef float f32x2 __attribute__((ext_vector_type(2)));
;                 const float r = rs[ai][m]; const float r2s = r * r, rls = r * -1.44269504f; const f32x2 r2 = {r2s, r2s}, rl = {rls, rls};
;                 unsigned hw[4];
; #pragma unroll
;                 for (int q = 0; q < 4; ++q) {
;                     const f32x4 gq = acc[ai][0][m][q >> 1], uq = acc[ai][1][m][q >> 1];
;                     const f32x2 g2 = {gq[2 * (q & 1)], gq[2 * (q & 1) + 1]}, u2 = {uq[2 * (q & 1)], uq[2 * (q & 1) + 1]};
;                     const f32x2 t = g2 * rl; f32x2 e; e.x = __builtin_amdgcn_exp2f(t.x); e.y = __builtin_amdgcn_exp2f(t.y);
;                     const f32x2 d = e + 1.0f; f32x2 rc; rc.x = __builtin_amdgcn_rcpf(d.x); rc.y = __builtin_amdgcn_rcpf(d.y);
;                     const f32x2 hv = ((g2 * u2) * r2) * rc;
;                     hw[q] = pk2(hv.x, hv.y);
;                 }
;                 u32x4 w; w.x = hw[0]; w.y = hw[1]; w.z = hw[2]; w.w = hw[3];
;                 *(u32x4*)(H + (size_t)(row0 + ai * 128 + m * 16) * DFF + col0) = w;
	v_rcp_f32_e32 v103, v103
	v_rcp_f32_e32 v94, v94
	v_rcp_f32_e32 v95, v95
	v_lshl_add_u64 v[98:99], v[98:99], 0, v[116:117]
	global_store_dwordx4 v[98:99], v[106:109], off
	v_mul_f32_e32 v98, v157, v157
	v_pk_mul_f32 v[90:91], v[90:91], v[98:99] op_sel_hi:[1,0]
	v_pk_mul_f32 v[92:93], v[92:93], v[98:99] op_sel_hi:[1,0]
	v_pk_mul_f32 v[90:91], v[90:91], v[102:103]
	v_pk_mul_f32 v[92:93], v[92:93], v[94:95]
	v_cvt_pk_bf16_f32 v90, v90, v91
	v_cvt_pk_bf16_f32 v91, v92, v93
	v_pk_mul_f32 v[92:93], v[86:87], v[100:101] op_sel_hi:[1,0]
	v_pk_mul_f32 v[82:83], v[82:83], v[98:99] op_sel_hi:[1,0]
	v_exp_f32_e32 v92, v92
	v_exp_f32_e32 v93, v93
	v_pk_mul_f32 v[84:85], v[84:85], v[98:99] op_sel_hi:[1,0]
	v_pk_add_f32 v[92:93], v[92:93], 1.0 op_sel_hi:[1,0]
	s_nop 0
	v_rcp_f32_e32 v92, v92
	v_rcp_f32_e32 v93, v93
	s_nop 0
	v_pk_mul_f32 v[82:83], v[82:83], v[92:93]
	s_nop 0
	v_cvt_pk_bf16_f32 v92, v82, v83
	v_pk_mul_f32 v[82:83], v[88:89], v[100:101] op_sel_hi:[1,0]
	s_nop 0
	v_exp_f32_e32 v82, v82
	v_exp_f32_e32 v83, v83
	s_nop 0
	v_pk_add_f32 v[82:83], v[82:83], 1.0 op_sel_hi:[1,0]
	s_nop 0
	v_rcp_f32_e32 v82, v82
	v_rcp_f32_e32 v83, v83
	s_nop 0
	v_pk_mul_f32 v[82:83], v[84:85], v[82:83]
	v_mul_f32_e32 v84, 0xbfb8aa3b, v155
	v_pk_mul_f32 v[86:87], v[78:79], v[84:85] op_sel_hi:[1,0]
	v_pk_mul_f32 v[78:79], v[80:81], v[84:85] op_sel_hi:[1,0]
	v_exp_f32_e32 v86, v86
	v_exp_f32_e32 v87, v87
	v_exp_f32_e32 v78, v78
	v_exp_f32_e32 v79, v79
	v_cvt_pk_bf16_f32 v93, v82, v83
	v_pk_add_f32 v[86:87], v[86:87], 1.0 op_sel_hi:[1,0]
	v_mad_i64_i32 v[82:83], s[2:3], v156, s27, v[114:115]
	v_pk_add_f32 v[78:79], v[78:79], 1.0 op_sel_hi:[1,0]
	v_rcp_f32_e32 v86, v86
	v_rcp_f32_e32 v87, v87
	v_rcp_f32_e32 v78, v78
	v_rcp_f32_e32 v79, v79
	v_lshl_add_u64 v[82:83], v[82:83], 0, v[116:117]
	global_store_dwordx4 v[82:83], v[90:93], off
	v_mul_f32_e32 v82, v155, v155
	v_pk_mul_f32 v[74:75], v[74:75], v[82:83] op_sel_hi:[1,0]
	v_pk_mul_f32 v[76:77], v[76:77], v[82:83] op_sel_hi:[1,0]
	v_pk_mul_f32 v[74:75], v[74:75], v[86:87]
	v_pk_mul_f32 v[76:77], v[76:77], v[78:79]
	v_cvt_pk_bf16_f32 v74, v74, v75
	v_cvt_pk_bf16_f32 v75, v76, v77
	v_pk_mul_f32 v[76:77], v[70:71], v[84:85] op_sel_hi:[1,0]
	v_pk_mul_f32 v[66:67], v[66:67], v[82:83] op_sel_hi:[1,0]
	v_exp_f32_e32 v76, v76
	v_exp_f32_e32 v77, v77
	v_pk_mul_f32 v[68:69], v[68:69], v[82:83] op_sel_hi:[1,0]
	v_pk_add_f32 v[76:77], v[76:77], 1.0 op_sel_hi:[1,0]
	s_nop 0
	v_rcp_f32_e32 v76, v76
	v_rcp_f32_e32 v77, v77
	s_nop 0
	v_pk_mul_f32 v[66:67], v[66:67], v[76:77]
	s_nop 0
	v_cvt_pk_bf16_f32 v76, v66, v67
	v_pk_mul_f32 v[66:67], v[72:73], v[84:85] op_sel_hi:[1,0]
	s_nop 0
	v_exp_f32_e32 v66, v66
	v_exp_f32_e32 v67, v67
	s_nop 0
	v_pk_add_f32 v[66:67], v[66:67], 1.0 op_sel_hi:[1,0]
	s_nop 0
	v_rcp_f32_e32 v66, v66
	v_rcp_f32_e32 v67, v67
	s_nop 0
	v_pk_mul_f32 v[66:67], v[68:69], v[66:67]
	v_mul_f32_e32 v68, 0xbfb8aa3b, v153
	v_pk_mul_f32 v[70:71], v[62:63], v[68:69] op_sel_hi:[1,0]
	v_pk_mul_f32 v[62:63], v[64:65], v[68:69] op_sel_hi:[1,0]
	v_exp_f32_e32 v70, v70
	v_exp_f32_e32 v71, v71
	v_exp_f32_e32 v62, v62
	v_exp_f32_e32 v63, v63
	v_cvt_pk_bf16_f32 v77, v66, v67
	v_pk_add_f32 v[70:71], v[70:71], 1.0 op_sel_hi:[1,0]
	v_mad_i64_i32 v[66:67], s[2:3], v154, s27, v[114:115]
	v_pk_add_f32 v[62:63], v[62:63], 1.0 op_sel_hi:[1,0]
	v_rcp_f32_e32 v70, v70
	v_rcp_f32_e32 v71, v71
	v_rcp_f32_e32 v62, v62
	v_rcp_f32_e32 v63, v63
	v_lshl_add_u64 v[66:67], v[66:67], 0, v[116:117]
	global_store_dwordx4 v[66:67], v[74:77], off
	v_mul_f32_e32 v66, v153, v153
	v_pk_mul_f32 v[58:59], v[58:59], v[66:67] op_sel_hi:[1,0]
	v_pk_mul_f32 v[60:61], v[60:61], v[66:67] op_sel_hi:[1,0]
	v_pk_mul_f32 v[58:59], v[58:59], v[70:71]
	v_pk_mul_f32 v[60:61], v[60:61], v[62:63]
	v_cvt_pk_bf16_f32 v58, v58, v59
	v_cvt_pk_bf16_f32 v59, v60, v61
	v_pk_mul_f32 v[60:61], v[54:55], v[68:69] op_sel_hi:[1,0]
	v_pk_mul_f32 v[50:51], v[50:51], v[66:67] op_sel_hi:[1,0]
	v_exp_f32_e32 v60, v60
	v_exp_f32_e32 v61, v61
	v_pk_mul_f32 v[52:53], v[52:53], v[66:67] op_sel_hi:[1,0]
	v_pk_add_f32 v[60:61], v[60:61], 1.0 op_sel_hi:[1,0]
	s_nop 0
	v_rcp_f32_e32 v60, v60
	v_rcp_f32_e32 v61, v61
	s_nop 0
	v_pk_mul_f32 v[50:51], v[50:51], v[60:61]
	s_nop 0
	v_cvt_pk_bf16_f32 v60, v50, v51
	v_pk_mul_f32 v[50:51], v[56:57], v[68:69] op_sel_hi:[1,0]
	s_nop 0
	v_exp_f32_e32 v50, v50
	v_exp_f32_e32 v51, v51
	s_nop 0
	v_pk_add_f32 v[50:51], v[50:51], 1.0 op_sel_hi:[1,0]
	s_nop 0
	v_rcp_f32_e32 v50, v50
	v_rcp_f32_e32 v51, v51
	s_nop 0
	v_pk_mul_f32 v[50:51], v[52:53], v[50:51]
	v_mul_f32_e32 v52, 0xbfb8aa3b, v151
	v_pk_mul_f32 v[54:55], v[46:47], v[52:53] op_sel_hi:[1,0]
	v_pk_mul_f32 v[46:47], v[48:49], v[52:53] op_sel_hi:[1,0]
	v_exp_f32_e32 v54, v54
	v_exp_f32_e32 v55, v55
	v_exp_f32_e32 v46, v46
	v_exp_f32_e32 v47, v47
	v_cvt_pk_bf16_f32 v61, v50, v51
	v_pk_add_f32 v[54:55], v[54:55], 1.0 op_sel_hi:[1,0]
	v_mad_i64_i32 v[50:51], s[2:3], v152, s27, v[114:115]
; DI unsigned pk2(float lo, float hi) { return pg8::cvt_pk_bf16(lo, hi); }
;     DI void operator()(const f32x4 (&acc)[2][2][4][2], const pg8::Unit& u, int wr, int wc, int fr, int fq) const {
;     ...
;             for (int m = 0; m < 4; ++m) {
;                 typedef float f32x2 __attribute__((ext_vector_type(2)));
;                 const float r = rs[ai][m]; const float r2s = r * r, rls = r * -1.44269504f; const f32x2 r2 = {r2s, r2s}, rl = {rls, rls};
;                 unsigned hw[4];
; #pragma unroll
;                 for (int q = 0; q < 4; ++q) {
;                     const f32x4 gq = acc[ai][0][m][q >> 1], uq = acc[ai][1][m][q >> 1];
;                     const f32x2 g2 = {gq[2 * (q & 1)], gq[2 * (q & 1) + 1]}, u2 = {uq[2 * (q & 1)], uq[2 * (q & 1) + 1]};
;                     const f32x2 t = g2 * rl; f32x2 e; e.x = __builtin_amdgcn_exp2f(t.x); e.y = __builtin_amdgcn_exp2f(t.y);
;                     const f32x2 d = e + 1.0f; f32x2 rc; rc.x = __builtin_amdgcn_rcpf(d.x); rc.y = __builtin_amdgcn_rcpf(d.y);
;                     const f32x2 hv = ((g2 * u2) * r2) * rc;
;                     hw[q] = pk2(hv.x, hv.y);
;                 }
;                 u32x4 w; w.x = hw[0]; w.y = hw[1]; w.z = hw[2]; w.w = hw[3];
;                 *(u32x4*)(H + (size_t)(row0 + ai * 128 + m * 16) * DFF + col0) = w;
	v_pk_add_f32 v[46:47], v[46:47], 1.0 op_sel_hi:[1,0]
	v_rcp_f32_e32 v54, v54
	v_rcp_f32_e32 v55, v55
	v_rcp_f32_e32 v46, v46
	v_rcp_f32_e32 v47, v47
	v_lshl_add_u64 v[50:51], v[50:51], 0, v[116:117]
	global_store_dwordx4 v[50:51], v[58:61], off
	v_mul_f32_e32 v50, v151, v151
	v_pk_mul_f32 v[42:43], v[42:43], v[50:51] op_sel_hi:[1,0]
	v_pk_mul_f32 v[44:45], v[44:45], v[50:51] op_sel_hi:[1,0]
	v_pk_mul_f32 v[42:43], v[42:43], v[54:55]
	v_pk_mul_f32 v[44:45], v[44:45], v[46:47]
	v_cvt_pk_bf16_f32 v42, v42, v43
	v_cvt_pk_bf16_f32 v43, v44, v45
	v_pk_mul_f32 v[44:45], v[38:39], v[52:53] op_sel_hi:[1,0]
	v_pk_mul_f32 v[34:35], v[34:35], v[50:51] op_sel_hi:[1,0]
	v_exp_f32_e32 v44, v44
	v_exp_f32_e32 v45, v45
	v_pk_mul_f32 v[36:37], v[36:37], v[50:51] op_sel_hi:[1,0]
	v_pk_add_f32 v[44:45], v[44:45], 1.0 op_sel_hi:[1,0]
	s_nop 0
	v_rcp_f32_e32 v44, v44
	v_rcp_f32_e32 v45, v45
	s_nop 0
	v_pk_mul_f32 v[34:35], v[34:35], v[44:45]
	s_nop 0
	v_cvt_pk_bf16_f32 v44, v34, v35
	v_pk_mul_f32 v[34:35], v[40:41], v[52:53] op_sel_hi:[1,0]
	s_nop 0
	v_exp_f32_e32 v34, v34
	v_exp_f32_e32 v35, v35
	s_nop 0
	v_pk_add_f32 v[34:35], v[34:35], 1.0 op_sel_hi:[1,0]
	s_nop 0
	v_rcp_f32_e32 v34, v34
	v_rcp_f32_e32 v35, v35
	s_nop 0
	v_pk_mul_f32 v[34:35], v[36:37], v[34:35]
	v_mul_f32_e32 v36, 0xbfb8aa3b, v131
	v_pk_mul_f32 v[38:39], v[30:31], v[36:37] op_sel_hi:[1,0]
	v_pk_mul_f32 v[30:31], v[32:33], v[36:37] op_sel_hi:[1,0]
	v_exp_f32_e32 v38, v38
	v_exp_f32_e32 v39, v39
	v_exp_f32_e32 v30, v30
	v_exp_f32_e32 v31, v31
	v_cvt_pk_bf16_f32 v45, v34, v35
	v_pk_add_f32 v[38:39], v[38:39], 1.0 op_sel_hi:[1,0]
	v_mad_i64_i32 v[34:35], s[2:3], v150, s27, v[114:115]
	v_pk_add_f32 v[30:31], v[30:31], 1.0 op_sel_hi:[1,0]
	v_rcp_f32_e32 v38, v38
	v_rcp_f32_e32 v39, v39
	v_rcp_f32_e32 v30, v30
	v_rcp_f32_e32 v31, v31
	v_lshl_add_u64 v[34:35], v[34:35], 0, v[116:117]
	global_store_dwordx4 v[34:35], v[42:45], off
	v_mul_f32_e32 v34, v131, v131
	v_pk_mul_f32 v[26:27], v[26:27], v[34:35] op_sel_hi:[1,0]
	v_pk_mul_f32 v[28:29], v[28:29], v[34:35] op_sel_hi:[1,0]
	v_pk_mul_f32 v[26:27], v[26:27], v[38:39]
	v_pk_mul_f32 v[28:29], v[28:29], v[30:31]
	v_cvt_pk_bf16_f32 v26, v26, v27
	v_cvt_pk_bf16_f32 v27, v28, v29
	v_pk_mul_f32 v[28:29], v[22:23], v[36:37] op_sel_hi:[1,0]
	v_pk_mul_f32 v[18:19], v[18:19], v[34:35] op_sel_hi:[1,0]
	v_exp_f32_e32 v28, v28
	v_exp_f32_e32 v29, v29
	v_pk_mul_f32 v[20:21], v[20:21], v[34:35] op_sel_hi:[1,0]
	v_pk_add_f32 v[28:29], v[28:29], 1.0 op_sel_hi:[1,0]
	s_nop 0
	v_rcp_f32_e32 v28, v28
	v_rcp_f32_e32 v29, v29
	s_nop 0
	v_pk_mul_f32 v[18:19], v[18:19], v[28:29]
	s_nop 0
	v_cvt_pk_bf16_f32 v28, v18, v19
	v_pk_mul_f32 v[18:19], v[24:25], v[36:37] op_sel_hi:[1,0]
	s_nop 0
	v_exp_f32_e32 v18, v18
	v_exp_f32_e32 v19, v19
	s_nop 0
	v_pk_add_f32 v[18:19], v[18:19], 1.0 op_sel_hi:[1,0]
	s_nop 0
	v_rcp_f32_e32 v18, v18
	v_rcp_f32_e32 v19, v19
	s_nop 0
	v_pk_mul_f32 v[18:19], v[20:21], v[18:19]
	v_mul_f32_e32 v20, 0xbfb8aa3b, v130
	v_pk_mul_f32 v[22:23], v[14:15], v[20:21] op_sel_hi:[1,0]
	v_pk_mul_f32 v[14:15], v[16:17], v[20:21] op_sel_hi:[1,0]
	v_exp_f32_e32 v22, v22
	v_exp_f32_e32 v23, v23
	v_exp_f32_e32 v14, v14
	v_exp_f32_e32 v15, v15
	v_cvt_pk_bf16_f32 v29, v18, v19
	v_pk_add_f32 v[22:23], v[22:23], 1.0 op_sel_hi:[1,0]
	v_mad_i64_i32 v[18:19], s[2:3], v148, s27, v[114:115]
	v_pk_add_f32 v[14:15], v[14:15], 1.0 op_sel_hi:[1,0]
	v_rcp_f32_e32 v22, v22
	v_rcp_f32_e32 v23, v23
	v_rcp_f32_e32 v14, v14
	v_rcp_f32_e32 v15, v15
	v_lshl_add_u64 v[18:19], v[18:19], 0, v[116:117]
	global_store_dwordx4 v[18:19], v[26:29], off
	v_mul_f32_e32 v18, v130, v130
	v_pk_mul_f32 v[10:11], v[10:11], v[18:19] op_sel_hi:[1,0]
	v_pk_mul_f32 v[12:13], v[12:13], v[18:19] op_sel_hi:[1,0]
	v_pk_mul_f32 v[10:11], v[10:11], v[22:23]
	v_pk_mul_f32 v[12:13], v[12:13], v[14:15]
	v_cvt_pk_bf16_f32 v10, v10, v11
	v_cvt_pk_bf16_f32 v11, v12, v13
	v_pk_mul_f32 v[12:13], v[6:7], v[20:21] op_sel_hi:[1,0]
	v_pk_mul_f32 v[2:3], v[2:3], v[18:19] op_sel_hi:[1,0]
	v_exp_f32_e32 v12, v12
	v_exp_f32_e32 v13, v13
	v_pk_mul_f32 v[4:5], v[4:5], v[18:19] op_sel_hi:[1,0]
	v_pk_add_f32 v[12:13], v[12:13], 1.0 op_sel_hi:[1,0]
	s_nop 0
	v_rcp_f32_e32 v12, v12
	v_rcp_f32_e32 v13, v13
	s_nop 0
	v_pk_mul_f32 v[2:3], v[2:3], v[12:13]
	s_nop 0
	v_cvt_pk_bf16_f32 v12, v2, v3
	v_pk_mul_f32 v[2:3], v[8:9], v[20:21] op_sel_hi:[1,0]
	s_nop 0
	v_exp_f32_e32 v2, v2
	v_exp_f32_e32 v3, v3
	s_nop 0
	v_pk_add_f32 v[2:3], v[2:3], 1.0 op_sel_hi:[1,0]
	s_nop 0
	v_rcp_f32_e32 v2, v2
	v_rcp_f32_e32 v3, v3
	s_nop 0
	v_pk_mul_f32 v[2:3], v[4:5], v[2:3]
	s_nop 0
	v_cvt_pk_bf16_f32 v13, v2, v3
	v_mad_i64_i32 v[2:3], s[2:3], v146, s27, v[114:115]
	v_lshl_add_u64 v[2:3], v[2:3], 0, v[116:117]
	s_mov_b64 s[2:3], -1
	global_store_dwordx4 v[2:3], v[10:13], off
	s_cbranch_vccnz .LBB0_1118
	s_andn2_b64 vcc, exec, s[42:43]
	s_cbranch_vccnz .LBB0_1117
	s_barrier
	s_branch .LBB0_1117

; __global__ void __launch_bounds__(NWAVES * 64, 2) fwd_megakernel(Args A) {
;     extern __shared__ __attribute__((aligned(16))) unsigned char lds[];
	.amdhsa_kernel _Z14fwd_megakernel4Args
		.amdhsa_group_segment_fixed_size 0
		.amdhsa_private_segment_fixed_size 0
		.amdhsa_kernarg_size 432
		.amdhsa_user_sgpr_count 2
		.amdhsa_user_sgpr_dispatch_ptr 0
		.amdhsa_user_sgpr_queue_ptr 0
		.amdhsa_user_sgpr_kernarg_segment_ptr 1
		.amdhsa_user_sgpr_dispatch_id 0
		.amdhsa_user_sgpr_kernarg_preload_length 0
		.amdhsa_user_sgpr_kernarg_preload_offset 0
		.amdhsa_user_sgpr_private_segment_size 0
		.amdhsa_uses_dynamic_stack 0
		.amdhsa_enable_private_segment 0
		.amdhsa_system_sgpr_workgroup_id_x 1
		.amdhsa_system_sgpr_workgroup_id_y 0
		.amdhsa_system_sgpr_workgroup_id_z 0
		.amdhsa_system_sgpr_workgroup_info 0
		.amdhsa_system_vgpr_workitem_id 2
		.amdhsa_next_free_vgpr 256
		.amdhsa_next_free_sgpr 100
		.amdhsa_accum_offset 248
		.amdhsa_reserve_vcc 1
		.amdhsa_float_round_mode_32 0
		.amdhsa_float_round_mode_16_64 0
		.amdhsa_float_denorm_mode_32 3
		.amdhsa_float_denorm_mode_16_64 3
		.amdhsa_dx10_clamp 1
		.amdhsa_ieee_mode 1
		.amdhsa_fp16_overflow 0
		.amdhsa_tg_split 0
		.amdhsa_exception_fp_ieee_invalid_op 0
		.amdhsa_exception_fp_denorm_src 0
		.amdhsa_exception_fp_ieee_div_zero 0
		.amdhsa_exception_fp_ieee_overflow 0
		.amdhsa_exception_fp_ieee_underflow 0
		.amdhsa_exception_fp_ieee_inexact 0
		.amdhsa_exception_int_div_zero 0
	.end_amdhsa_kernel

; __global__ void __launch_bounds__(NWAVES * 64, 2) fwd_megakernel(Args A) {
;     extern __shared__ __attribute__((aligned(16))) unsigned char lds[];
amdhsa.kernels:
  - .agpr_count:     0
    .args:
      - .offset:         0
        .size:           176
        .value_kind:     by_value
      - .offset:         176
        .size:           4
        .value_kind:     hidden_block_count_x
      - .offset:         180
        .size:           4
        .value_kind:     hidden_block_count_y
      - .offset:         184
        .size:           4
        .value_kind:     hidden_block_count_z
      - .offset:         188
        .size:           2
        .value_kind:     hidden_group_size_x
      - .offset:         190
        .size:           2
        .value_kind:     hidden_group_size_y
      - .offset:         192
        .size:           2
        .value_kind:     hidden_group_size_z
      - .offset:         194
        .size:           2
        .value_kind:     hidden_remainder_x
      - .offset:         196
        .size:           2
        .value_kind:     hidden_remainder_y
      - .offset:         198
        .size:           2
        .value_kind:     hidden_remainder_z
      - .offset:         216
        .size:           8
        .value_kind:     hidden_global_offset_x
      - .offset:         224
        .size:           8
        .value_kind:     hidden_global_offset_y
      - .offset:         232
        .size:           8
        .value_kind:     hidden_global_offset_z
      - .offset:         240
        .size:           2
        .value_kind:     hidden_grid_dims
      - .offset:         264
        .size:           8
        .value_kind:     hidden_multigrid_sync_arg
      - .offset:         296
        .size:           4
        .value_kind:     hidden_dynamic_lds_size
    .group_segment_fixed_size: 0
    .kernarg_segment_align: 8
    .kernarg_segment_size: 432
    .language:       OpenCL C
    .language_version:
      - 2
      - 0
    .max_flat_workgroup_size: 512
    .name:           _Z14fwd_megakernel4Args
    .private_segment_fixed_size: 0
    .sgpr_count:     106
    .sgpr_spill_count: 155
    .symbol:         _Z14fwd_megakernel4Args.kd
    .uniform_work_group_size: 1
    .uses_dynamic_stack: false
    .vgpr_count:     256
    .vgpr_spill_count: 0
    .wavefront_size: 64
